# scan waves: counted waits grouped per operand (both halves at once, 49 fewer s_waitcnt per chunk) (gen_scan8.py), on v192
# speedup vs baseline: 1.0005x; 1.0005x over previous
.LBB0_390:
	s_and_b32 s3, s2, 1
	s_mul_i32 s8, s3, 0x5000
	v_add_u32_e32 v2, s8, v136
	s_mul_i32 s8, s2, 0xab
	s_bfe_u32 s8, s8, 0x70009
	s_mul_i32 s8, s8, 3
	s_sub_i32 s8, s2, s8
	s_and_b32 s8, s8, 0xff
	s_mulk_i32 s8, 0x1100
	v_add_u32_e32 v3, s8, v137
	v_lshl_add_u32 v1, s3, 12, v137
	ds_read_b128 v[176:179], v2 offset:4096
	ds_read_b128 v[180:183], v2 offset:4112
	ds_read_b128 v[200:203], v2 offset:12288
	ds_read_b128 v[204:207], v2 offset:12304
	ds_read_b64 v[216:217], v3 offset:40960
	ds_read_b128 v[184:187], v2 offset:0
	ds_read_b128 v[188:191], v2 offset:16
	ds_read_b128 v[192:195], v2 offset:8192
	ds_read_b128 v[196:199], v2 offset:8208
	s_waitcnt lgkmcnt(7)
	v_pk_mul_f32 v[164:165], v[72:73], v[176:177]
	v_pk_mul_f32 v[166:167], v[80:81], v[176:177]
	ds_read_b128 v[208:211], v2 offset:16384
	v_pk_fma_f32 v[164:165], v[74:75], v[178:179], v[164:165]
	v_pk_fma_f32 v[166:167], v[82:83], v[178:179], v[166:167]
	ds_read_b128 v[212:215], v2 offset:16400
	v_pk_fma_f32 v[164:165], v[76:77], v[180:181], v[164:165]
	v_pk_fma_f32 v[166:167], v[84:85], v[180:181], v[166:167]
	ds_read_b128 v[4:7], v2 offset:4352
	v_pk_fma_f32 v[164:165], v[78:79], v[182:183], v[164:165]
	v_pk_fma_f32 v[166:167], v[86:87], v[182:183], v[166:167]
	ds_read_b128 v[8:11], v2 offset:4368
	s_waitcnt lgkmcnt(8)
	v_pk_mul_f32 v[218:219], v[216:217], v[200:201] op_sel_hi:[0,1]
	v_pk_mul_f32 v[226:227], v[216:217], v[200:201] op_sel:[1,0]
	ds_read_b128 v[40:43], v2 offset:12544
	v_pk_mul_f32 v[220:221], v[216:217], v[202:203] op_sel_hi:[0,1]
	v_pk_mul_f32 v[228:229], v[216:217], v[202:203] op_sel:[1,0]
	ds_read_b128 v[44:47], v2 offset:12560
	v_pk_mul_f32 v[222:223], v[216:217], v[204:205] op_sel_hi:[0,1]
	v_pk_mul_f32 v[230:231], v[216:217], v[204:205] op_sel:[1,0]
	ds_read_b64 v[26:27], v3 offset:41216
	v_pk_mul_f32 v[224:225], v[216:217], v[206:207] op_sel_hi:[0,1]
	v_pk_mul_f32 v[234:235], v[216:217], v[206:207] op_sel:[1,0]
	ds_read_b128 v[12:15], v2 offset:256
	v_add_f32_e32 v172, v164, v165
	v_add_f32_e32 v174, v166, v167
	ds_read_b128 v[28:31], v2 offset:272
	s_waitcnt lgkmcnt(11)
	v_pk_fma_f32 v[218:219], v[72:73], v[184:185], v[218:219]
	v_pk_fma_f32 v[226:227], v[80:81], v[184:185], v[226:227]
	ds_read_b128 v[32:35], v2 offset:8448
	v_pk_fma_f32 v[220:221], v[74:75], v[186:187], v[220:221]
	v_pk_fma_f32 v[228:229], v[82:83], v[186:187], v[228:229]
	ds_read_b128 v[36:39], v2 offset:8464
	v_add_f32_dpp v172, v172, v172 quad_perm:[1,0,3,2] row_mask:0xf bank_mask:0xf bound_ctrl:1
	v_add_f32_dpp v174, v174, v174 quad_perm:[1,0,3,2] row_mask:0xf bank_mask:0xf bound_ctrl:1
	v_pk_fma_f32 v[222:223], v[76:77], v[188:189], v[222:223]
	v_pk_fma_f32 v[230:231], v[84:85], v[188:189], v[230:231]
	v_pk_fma_f32 v[224:225], v[78:79], v[190:191], v[224:225]
	v_pk_fma_f32 v[234:235], v[86:87], v[190:191], v[234:235]
	v_add_f32_dpp v172, v172, v172 quad_perm:[2,3,0,1] row_mask:0xf bank_mask:0xf bound_ctrl:1
	v_add_f32_dpp v174, v174, v174 quad_perm:[2,3,0,1] row_mask:0xf bank_mask:0xf bound_ctrl:1
	s_nop 0
	v_add_f32_dpp v172, v172, v172 row_half_mirror row_mask:0xf bank_mask:0xf bound_ctrl:1
	v_add_f32_dpp v174, v174, v174 row_half_mirror row_mask:0xf bank_mask:0xf bound_ctrl:1
	s_waitcnt lgkmcnt(11)
	v_pk_fma_f32 v[72:73], v[192:193], v[172:173], v[218:219] op_sel_hi:[1,0,1]
	v_pk_fma_f32 v[80:81], v[192:193], v[174:175], v[226:227] op_sel_hi:[1,0,1]
	v_pk_fma_f32 v[74:75], v[194:195], v[172:173], v[220:221] op_sel_hi:[1,0,1]
	v_pk_fma_f32 v[82:83], v[194:195], v[174:175], v[228:229] op_sel_hi:[1,0,1]
	v_pk_fma_f32 v[76:77], v[196:197], v[172:173], v[222:223] op_sel_hi:[1,0,1]
	v_pk_fma_f32 v[84:85], v[196:197], v[174:175], v[230:231] op_sel_hi:[1,0,1]
	v_pk_fma_f32 v[78:79], v[198:199], v[172:173], v[224:225] op_sel_hi:[1,0,1]
	v_pk_fma_f32 v[86:87], v[198:199], v[174:175], v[234:235] op_sel_hi:[1,0,1]
	s_waitcnt lgkmcnt(7)
	v_pk_mul_f32 v[164:165], v[72:73], v[4:5]
	v_pk_mul_f32 v[166:167], v[80:81], v[4:5]
	ds_read_b128 v[48:51], v2 offset:16640
	v_pk_mul_f32 v[168:169], v[72:73], v[208:209]
	v_pk_mul_f32 v[170:171], v[80:81], v[208:209]
	ds_read_b128 v[52:55], v2 offset:16656
	v_pk_fma_f32 v[164:165], v[74:75], v[6:7], v[164:165]
	v_pk_fma_f32 v[166:167], v[82:83], v[6:7], v[166:167]
	ds_read_b128 v[176:179], v2 offset:4608
	v_pk_fma_f32 v[168:169], v[74:75], v[210:211], v[168:169]
	v_pk_fma_f32 v[170:171], v[82:83], v[210:211], v[170:171]
	ds_read_b128 v[180:183], v2 offset:4624
	v_pk_fma_f32 v[164:165], v[76:77], v[8:9], v[164:165]
	v_pk_fma_f32 v[166:167], v[84:85], v[8:9], v[166:167]
	ds_read_b128 v[200:203], v2 offset:12800
	v_pk_fma_f32 v[168:169], v[76:77], v[212:213], v[168:169]
	v_pk_fma_f32 v[170:171], v[84:85], v[212:213], v[170:171]
	ds_read_b128 v[204:207], v2 offset:12816
	v_pk_fma_f32 v[164:165], v[78:79], v[10:11], v[164:165]
	v_pk_fma_f32 v[166:167], v[86:87], v[10:11], v[166:167]
	ds_read_b64 v[216:217], v3 offset:41472
	v_pk_fma_f32 v[168:169], v[78:79], v[214:215], v[168:169]
	v_pk_fma_f32 v[170:171], v[86:87], v[214:215], v[170:171]
	ds_read_b128 v[184:187], v2 offset:512
	s_waitcnt lgkmcnt(12)
	v_pk_mul_f32 v[218:219], v[26:27], v[40:41] op_sel_hi:[0,1]
	v_pk_mul_f32 v[226:227], v[26:27], v[40:41] op_sel:[1,0]
	ds_read_b128 v[188:191], v2 offset:528
	v_pk_mul_f32 v[220:221], v[26:27], v[42:43] op_sel_hi:[0,1]
	v_pk_mul_f32 v[228:229], v[26:27], v[42:43] op_sel:[1,0]
	ds_read_b128 v[192:195], v2 offset:8704
	v_pk_mul_f32 v[222:223], v[26:27], v[44:45] op_sel_hi:[0,1]
	v_pk_mul_f32 v[230:231], v[26:27], v[44:45] op_sel:[1,0]
	ds_read_b128 v[196:199], v2 offset:8720
	v_pk_mul_f32 v[224:225], v[26:27], v[46:47] op_sel_hi:[0,1]
	v_pk_mul_f32 v[234:235], v[26:27], v[46:47] op_sel:[1,0]
	v_add_f32_e32 v172, v164, v165
	v_add_f32_e32 v174, v166, v167
	v_add_f32_e32 v160, v168, v169
	v_add_f32_e32 v161, v170, v171
	s_waitcnt lgkmcnt(13)
	v_pk_fma_f32 v[218:219], v[72:73], v[12:13], v[218:219]
	v_pk_fma_f32 v[226:227], v[80:81], v[12:13], v[226:227]
	v_pk_fma_f32 v[220:221], v[74:75], v[14:15], v[220:221]
	v_pk_fma_f32 v[228:229], v[82:83], v[14:15], v[228:229]
	v_add_f32_dpp v172, v172, v172 quad_perm:[1,0,3,2] row_mask:0xf bank_mask:0xf bound_ctrl:1
	v_add_f32_dpp v174, v174, v174 quad_perm:[1,0,3,2] row_mask:0xf bank_mask:0xf bound_ctrl:1
	v_add_f32_dpp v160, v160, v160 quad_perm:[1,0,3,2] row_mask:0xf bank_mask:0xf bound_ctrl:1
	v_add_f32_dpp v161, v161, v161 quad_perm:[1,0,3,2] row_mask:0xf bank_mask:0xf bound_ctrl:1
	v_pk_fma_f32 v[222:223], v[76:77], v[28:29], v[222:223]
	v_pk_fma_f32 v[230:231], v[84:85], v[28:29], v[230:231]
	v_pk_fma_f32 v[224:225], v[78:79], v[30:31], v[224:225]
	v_pk_fma_f32 v[234:235], v[86:87], v[30:31], v[234:235]
	v_add_f32_dpp v172, v172, v172 quad_perm:[2,3,0,1] row_mask:0xf bank_mask:0xf bound_ctrl:1
	v_add_f32_dpp v174, v174, v174 quad_perm:[2,3,0,1] row_mask:0xf bank_mask:0xf bound_ctrl:1
	v_add_f32_dpp v160, v160, v160 quad_perm:[2,3,0,1] row_mask:0xf bank_mask:0xf bound_ctrl:1
	v_add_f32_dpp v161, v161, v161 quad_perm:[2,3,0,1] row_mask:0xf bank_mask:0xf bound_ctrl:1
	v_add_f32_dpp v172, v172, v172 row_half_mirror row_mask:0xf bank_mask:0xf bound_ctrl:1
	v_add_f32_dpp v174, v174, v174 row_half_mirror row_mask:0xf bank_mask:0xf bound_ctrl:1
	v_add_f32_dpp v160, v160, v160 row_half_mirror row_mask:0xf bank_mask:0xf bound_ctrl:1
	v_add_f32_dpp v161, v161, v161 row_half_mirror row_mask:0xf bank_mask:0xf bound_ctrl:1
	s_waitcnt lgkmcnt(11)
	v_pk_fma_f32 v[72:73], v[32:33], v[172:173], v[218:219] op_sel_hi:[1,0,1]
	v_pk_fma_f32 v[80:81], v[32:33], v[174:175], v[226:227] op_sel_hi:[1,0,1]
	v_pk_fma_f32 v[74:75], v[34:35], v[172:173], v[220:221] op_sel_hi:[1,0,1]
	v_pk_fma_f32 v[82:83], v[34:35], v[174:175], v[228:229] op_sel_hi:[1,0,1]
	v_pk_fma_f32 v[76:77], v[36:37], v[172:173], v[222:223] op_sel_hi:[1,0,1]
	v_pk_fma_f32 v[84:85], v[36:37], v[174:175], v[230:231] op_sel_hi:[1,0,1]
	v_pk_fma_f32 v[78:79], v[38:39], v[172:173], v[224:225] op_sel_hi:[1,0,1]
	v_pk_fma_f32 v[86:87], v[38:39], v[174:175], v[234:235] op_sel_hi:[1,0,1]
	ds_write_b64 v1, v[160:161] offset:54016
	s_waitcnt lgkmcnt(8)
	v_pk_mul_f32 v[164:165], v[72:73], v[176:177]
	v_pk_mul_f32 v[166:167], v[80:81], v[176:177]
	ds_read_b128 v[208:211], v2 offset:16896
	v_pk_mul_f32 v[168:169], v[72:73], v[48:49]
	v_pk_mul_f32 v[170:171], v[80:81], v[48:49]
	ds_read_b128 v[212:215], v2 offset:16912
	v_pk_fma_f32 v[164:165], v[74:75], v[178:179], v[164:165]
	v_pk_fma_f32 v[166:167], v[82:83], v[178:179], v[166:167]
	ds_read_b128 v[4:7], v2 offset:4864
	v_pk_fma_f32 v[168:169], v[74:75], v[50:51], v[168:169]
	v_pk_fma_f32 v[170:171], v[82:83], v[50:51], v[170:171]
	ds_read_b128 v[8:11], v2 offset:4880
	v_pk_fma_f32 v[164:165], v[76:77], v[180:181], v[164:165]
	v_pk_fma_f32 v[166:167], v[84:85], v[180:181], v[166:167]
	ds_read_b128 v[40:43], v2 offset:13056
	v_pk_fma_f32 v[168:169], v[76:77], v[52:53], v[168:169]
	v_pk_fma_f32 v[170:171], v[84:85], v[52:53], v[170:171]
	ds_read_b128 v[44:47], v2 offset:13072
	v_pk_fma_f32 v[164:165], v[78:79], v[182:183], v[164:165]
	v_pk_fma_f32 v[166:167], v[86:87], v[182:183], v[166:167]
	ds_read_b64 v[26:27], v3 offset:41728
	v_pk_fma_f32 v[168:169], v[78:79], v[54:55], v[168:169]
	v_pk_fma_f32 v[170:171], v[86:87], v[54:55], v[170:171]
	ds_read_b128 v[12:15], v2 offset:768
	s_waitcnt lgkmcnt(13)
	v_pk_mul_f32 v[218:219], v[216:217], v[200:201] op_sel_hi:[0,1]
	v_pk_mul_f32 v[226:227], v[216:217], v[200:201] op_sel:[1,0]
	ds_read_b128 v[28:31], v2 offset:784
	v_pk_mul_f32 v[220:221], v[216:217], v[202:203] op_sel_hi:[0,1]
	v_pk_mul_f32 v[228:229], v[216:217], v[202:203] op_sel:[1,0]
	ds_read_b128 v[32:35], v2 offset:8960
	v_pk_mul_f32 v[222:223], v[216:217], v[204:205] op_sel_hi:[0,1]
	v_pk_mul_f32 v[230:231], v[216:217], v[204:205] op_sel:[1,0]
	ds_read_b128 v[36:39], v2 offset:8976
	v_pk_mul_f32 v[224:225], v[216:217], v[206:207] op_sel_hi:[0,1]
	v_pk_mul_f32 v[234:235], v[216:217], v[206:207] op_sel:[1,0]
	v_add_f32_e32 v172, v164, v165
	v_add_f32_e32 v174, v166, v167
	v_add_f32_e32 v160, v168, v169
	v_add_f32_e32 v161, v170, v171
	s_waitcnt lgkmcnt(14)
	v_pk_fma_f32 v[218:219], v[72:73], v[184:185], v[218:219]
	v_pk_fma_f32 v[226:227], v[80:81], v[184:185], v[226:227]
	v_pk_fma_f32 v[220:221], v[74:75], v[186:187], v[220:221]
	v_pk_fma_f32 v[228:229], v[82:83], v[186:187], v[228:229]
	v_add_f32_dpp v172, v172, v172 quad_perm:[1,0,3,2] row_mask:0xf bank_mask:0xf bound_ctrl:1
	v_add_f32_dpp v174, v174, v174 quad_perm:[1,0,3,2] row_mask:0xf bank_mask:0xf bound_ctrl:1
	v_add_f32_dpp v160, v160, v160 quad_perm:[1,0,3,2] row_mask:0xf bank_mask:0xf bound_ctrl:1
	v_add_f32_dpp v161, v161, v161 quad_perm:[1,0,3,2] row_mask:0xf bank_mask:0xf bound_ctrl:1
	v_pk_fma_f32 v[222:223], v[76:77], v[188:189], v[222:223]
	v_pk_fma_f32 v[230:231], v[84:85], v[188:189], v[230:231]
	v_pk_fma_f32 v[224:225], v[78:79], v[190:191], v[224:225]
	v_pk_fma_f32 v[234:235], v[86:87], v[190:191], v[234:235]
	v_add_f32_dpp v172, v172, v172 quad_perm:[2,3,0,1] row_mask:0xf bank_mask:0xf bound_ctrl:1
	v_add_f32_dpp v174, v174, v174 quad_perm:[2,3,0,1] row_mask:0xf bank_mask:0xf bound_ctrl:1
	v_add_f32_dpp v160, v160, v160 quad_perm:[2,3,0,1] row_mask:0xf bank_mask:0xf bound_ctrl:1
	v_add_f32_dpp v161, v161, v161 quad_perm:[2,3,0,1] row_mask:0xf bank_mask:0xf bound_ctrl:1
	v_add_f32_dpp v172, v172, v172 row_half_mirror row_mask:0xf bank_mask:0xf bound_ctrl:1
	v_add_f32_dpp v174, v174, v174 row_half_mirror row_mask:0xf bank_mask:0xf bound_ctrl:1
	v_add_f32_dpp v160, v160, v160 row_half_mirror row_mask:0xf bank_mask:0xf bound_ctrl:1
	v_add_f32_dpp v161, v161, v161 row_half_mirror row_mask:0xf bank_mask:0xf bound_ctrl:1
	s_waitcnt lgkmcnt(12)
	v_pk_fma_f32 v[72:73], v[192:193], v[172:173], v[218:219] op_sel_hi:[1,0,1]
	v_pk_fma_f32 v[80:81], v[192:193], v[174:175], v[226:227] op_sel_hi:[1,0,1]
	v_pk_fma_f32 v[74:75], v[194:195], v[172:173], v[220:221] op_sel_hi:[1,0,1]
	v_pk_fma_f32 v[82:83], v[194:195], v[174:175], v[228:229] op_sel_hi:[1,0,1]
	v_pk_fma_f32 v[76:77], v[196:197], v[172:173], v[222:223] op_sel_hi:[1,0,1]
	v_pk_fma_f32 v[84:85], v[196:197], v[174:175], v[230:231] op_sel_hi:[1,0,1]
	v_pk_fma_f32 v[78:79], v[198:199], v[172:173], v[224:225] op_sel_hi:[1,0,1]
	v_pk_fma_f32 v[86:87], v[198:199], v[174:175], v[234:235] op_sel_hi:[1,0,1]
	ds_write_b64 v1, v[160:161] offset:54272
	s_waitcnt lgkmcnt(8)
	v_pk_mul_f32 v[164:165], v[72:73], v[4:5]
	v_pk_mul_f32 v[166:167], v[80:81], v[4:5]
	ds_read_b128 v[48:51], v2 offset:17152
	v_pk_mul_f32 v[168:169], v[72:73], v[208:209]
	v_pk_mul_f32 v[170:171], v[80:81], v[208:209]
	ds_read_b128 v[52:55], v2 offset:17168
	v_pk_fma_f32 v[164:165], v[74:75], v[6:7], v[164:165]
	v_pk_fma_f32 v[166:167], v[82:83], v[6:7], v[166:167]
	ds_read_b128 v[176:179], v2 offset:5120
	v_pk_fma_f32 v[168:169], v[74:75], v[210:211], v[168:169]
	v_pk_fma_f32 v[170:171], v[82:83], v[210:211], v[170:171]
	ds_read_b128 v[180:183], v2 offset:5136
	v_pk_fma_f32 v[164:165], v[76:77], v[8:9], v[164:165]
	v_pk_fma_f32 v[166:167], v[84:85], v[8:9], v[166:167]
	ds_read_b128 v[200:203], v2 offset:13312
	v_pk_fma_f32 v[168:169], v[76:77], v[212:213], v[168:169]
	v_pk_fma_f32 v[170:171], v[84:85], v[212:213], v[170:171]
	ds_read_b128 v[204:207], v2 offset:13328
	v_pk_fma_f32 v[164:165], v[78:79], v[10:11], v[164:165]
	v_pk_fma_f32 v[166:167], v[86:87], v[10:11], v[166:167]
	ds_read_b64 v[216:217], v3 offset:41984
	v_pk_fma_f32 v[168:169], v[78:79], v[214:215], v[168:169]
	v_pk_fma_f32 v[170:171], v[86:87], v[214:215], v[170:171]
	ds_read_b128 v[184:187], v2 offset:1024
	s_waitcnt lgkmcnt(13)
	v_pk_mul_f32 v[218:219], v[26:27], v[40:41] op_sel_hi:[0,1]
	v_pk_mul_f32 v[226:227], v[26:27], v[40:41] op_sel:[1,0]
	ds_read_b128 v[188:191], v2 offset:1040
	v_pk_mul_f32 v[220:221], v[26:27], v[42:43] op_sel_hi:[0,1]
	v_pk_mul_f32 v[228:229], v[26:27], v[42:43] op_sel:[1,0]
	ds_read_b128 v[192:195], v2 offset:9216
	v_pk_mul_f32 v[222:223], v[26:27], v[44:45] op_sel_hi:[0,1]
	v_pk_mul_f32 v[230:231], v[26:27], v[44:45] op_sel:[1,0]
	ds_read_b128 v[196:199], v2 offset:9232
	v_pk_mul_f32 v[224:225], v[26:27], v[46:47] op_sel_hi:[0,1]
	v_pk_mul_f32 v[234:235], v[26:27], v[46:47] op_sel:[1,0]
	v_add_f32_e32 v172, v164, v165
	v_add_f32_e32 v174, v166, v167
	v_add_f32_e32 v160, v168, v169
	v_add_f32_e32 v161, v170, v171
	s_waitcnt lgkmcnt(14)
	v_pk_fma_f32 v[218:219], v[72:73], v[12:13], v[218:219]
	v_pk_fma_f32 v[226:227], v[80:81], v[12:13], v[226:227]
	v_pk_fma_f32 v[220:221], v[74:75], v[14:15], v[220:221]
	v_pk_fma_f32 v[228:229], v[82:83], v[14:15], v[228:229]
	v_add_f32_dpp v172, v172, v172 quad_perm:[1,0,3,2] row_mask:0xf bank_mask:0xf bound_ctrl:1
	v_add_f32_dpp v174, v174, v174 quad_perm:[1,0,3,2] row_mask:0xf bank_mask:0xf bound_ctrl:1
	v_add_f32_dpp v160, v160, v160 quad_perm:[1,0,3,2] row_mask:0xf bank_mask:0xf bound_ctrl:1
	v_add_f32_dpp v161, v161, v161 quad_perm:[1,0,3,2] row_mask:0xf bank_mask:0xf bound_ctrl:1
	v_pk_fma_f32 v[222:223], v[76:77], v[28:29], v[222:223]
	v_pk_fma_f32 v[230:231], v[84:85], v[28:29], v[230:231]
	v_pk_fma_f32 v[224:225], v[78:79], v[30:31], v[224:225]
	v_pk_fma_f32 v[234:235], v[86:87], v[30:31], v[234:235]
	v_add_f32_dpp v172, v172, v172 quad_perm:[2,3,0,1] row_mask:0xf bank_mask:0xf bound_ctrl:1
	v_add_f32_dpp v174, v174, v174 quad_perm:[2,3,0,1] row_mask:0xf bank_mask:0xf bound_ctrl:1
	v_add_f32_dpp v160, v160, v160 quad_perm:[2,3,0,1] row_mask:0xf bank_mask:0xf bound_ctrl:1
	v_add_f32_dpp v161, v161, v161 quad_perm:[2,3,0,1] row_mask:0xf bank_mask:0xf bound_ctrl:1
	v_add_f32_dpp v172, v172, v172 row_half_mirror row_mask:0xf bank_mask:0xf bound_ctrl:1
	v_add_f32_dpp v174, v174, v174 row_half_mirror row_mask:0xf bank_mask:0xf bound_ctrl:1
	v_add_f32_dpp v160, v160, v160 row_half_mirror row_mask:0xf bank_mask:0xf bound_ctrl:1
	v_add_f32_dpp v161, v161, v161 row_half_mirror row_mask:0xf bank_mask:0xf bound_ctrl:1
	s_waitcnt lgkmcnt(12)
	v_pk_fma_f32 v[72:73], v[32:33], v[172:173], v[218:219] op_sel_hi:[1,0,1]
	v_pk_fma_f32 v[80:81], v[32:33], v[174:175], v[226:227] op_sel_hi:[1,0,1]
	v_pk_fma_f32 v[74:75], v[34:35], v[172:173], v[220:221] op_sel_hi:[1,0,1]
	v_pk_fma_f32 v[82:83], v[34:35], v[174:175], v[228:229] op_sel_hi:[1,0,1]
	v_pk_fma_f32 v[76:77], v[36:37], v[172:173], v[222:223] op_sel_hi:[1,0,1]
	v_pk_fma_f32 v[84:85], v[36:37], v[174:175], v[230:231] op_sel_hi:[1,0,1]
	v_pk_fma_f32 v[78:79], v[38:39], v[172:173], v[224:225] op_sel_hi:[1,0,1]
	v_pk_fma_f32 v[86:87], v[38:39], v[174:175], v[234:235] op_sel_hi:[1,0,1]
	ds_write_b64 v1, v[160:161] offset:54528
	s_waitcnt lgkmcnt(8)
	v_pk_mul_f32 v[164:165], v[72:73], v[176:177]
	v_pk_mul_f32 v[166:167], v[80:81], v[176:177]
	ds_read_b128 v[208:211], v2 offset:17408
	v_pk_mul_f32 v[168:169], v[72:73], v[48:49]
	v_pk_mul_f32 v[170:171], v[80:81], v[48:49]
	ds_read_b128 v[212:215], v2 offset:17424
	v_pk_fma_f32 v[164:165], v[74:75], v[178:179], v[164:165]
	v_pk_fma_f32 v[166:167], v[82:83], v[178:179], v[166:167]
	ds_read_b128 v[4:7], v2 offset:5376
	v_pk_fma_f32 v[168:169], v[74:75], v[50:51], v[168:169]
	v_pk_fma_f32 v[170:171], v[82:83], v[50:51], v[170:171]
	ds_read_b128 v[8:11], v2 offset:5392
	v_pk_fma_f32 v[164:165], v[76:77], v[180:181], v[164:165]
	v_pk_fma_f32 v[166:167], v[84:85], v[180:181], v[166:167]
	ds_read_b128 v[40:43], v2 offset:13568
	v_pk_fma_f32 v[168:169], v[76:77], v[52:53], v[168:169]
	v_pk_fma_f32 v[170:171], v[84:85], v[52:53], v[170:171]
	ds_read_b128 v[44:47], v2 offset:13584
	v_pk_fma_f32 v[164:165], v[78:79], v[182:183], v[164:165]
	v_pk_fma_f32 v[166:167], v[86:87], v[182:183], v[166:167]
	ds_read_b64 v[26:27], v3 offset:42240
	v_pk_fma_f32 v[168:169], v[78:79], v[54:55], v[168:169]
	v_pk_fma_f32 v[170:171], v[86:87], v[54:55], v[170:171]
	ds_read_b128 v[12:15], v2 offset:1280
	s_waitcnt lgkmcnt(13)
	v_pk_mul_f32 v[218:219], v[216:217], v[200:201] op_sel_hi:[0,1]
	v_pk_mul_f32 v[226:227], v[216:217], v[200:201] op_sel:[1,0]
	ds_read_b128 v[28:31], v2 offset:1296
	v_pk_mul_f32 v[220:221], v[216:217], v[202:203] op_sel_hi:[0,1]
	v_pk_mul_f32 v[228:229], v[216:217], v[202:203] op_sel:[1,0]
	ds_read_b128 v[32:35], v2 offset:9472
	v_pk_mul_f32 v[222:223], v[216:217], v[204:205] op_sel_hi:[0,1]
	v_pk_mul_f32 v[230:231], v[216:217], v[204:205] op_sel:[1,0]
	ds_read_b128 v[36:39], v2 offset:9488
	v_pk_mul_f32 v[224:225], v[216:217], v[206:207] op_sel_hi:[0,1]
	v_pk_mul_f32 v[234:235], v[216:217], v[206:207] op_sel:[1,0]
	v_add_f32_e32 v172, v164, v165
	v_add_f32_e32 v174, v166, v167
	v_add_f32_e32 v160, v168, v169
	v_add_f32_e32 v161, v170, v171
	s_waitcnt lgkmcnt(14)
	v_pk_fma_f32 v[218:219], v[72:73], v[184:185], v[218:219]
	v_pk_fma_f32 v[226:227], v[80:81], v[184:185], v[226:227]
	v_pk_fma_f32 v[220:221], v[74:75], v[186:187], v[220:221]
	v_pk_fma_f32 v[228:229], v[82:83], v[186:187], v[228:229]
	v_add_f32_dpp v172, v172, v172 quad_perm:[1,0,3,2] row_mask:0xf bank_mask:0xf bound_ctrl:1
	v_add_f32_dpp v174, v174, v174 quad_perm:[1,0,3,2] row_mask:0xf bank_mask:0xf bound_ctrl:1
	v_add_f32_dpp v160, v160, v160 quad_perm:[1,0,3,2] row_mask:0xf bank_mask:0xf bound_ctrl:1
	v_add_f32_dpp v161, v161, v161 quad_perm:[1,0,3,2] row_mask:0xf bank_mask:0xf bound_ctrl:1
	v_pk_fma_f32 v[222:223], v[76:77], v[188:189], v[222:223]
	v_pk_fma_f32 v[230:231], v[84:85], v[188:189], v[230:231]
	v_pk_fma_f32 v[224:225], v[78:79], v[190:191], v[224:225]
	v_pk_fma_f32 v[234:235], v[86:87], v[190:191], v[234:235]
	v_add_f32_dpp v172, v172, v172 quad_perm:[2,3,0,1] row_mask:0xf bank_mask:0xf bound_ctrl:1
	v_add_f32_dpp v174, v174, v174 quad_perm:[2,3,0,1] row_mask:0xf bank_mask:0xf bound_ctrl:1
	v_add_f32_dpp v160, v160, v160 quad_perm:[2,3,0,1] row_mask:0xf bank_mask:0xf bound_ctrl:1
	v_add_f32_dpp v161, v161, v161 quad_perm:[2,3,0,1] row_mask:0xf bank_mask:0xf bound_ctrl:1
	v_add_f32_dpp v172, v172, v172 row_half_mirror row_mask:0xf bank_mask:0xf bound_ctrl:1
	v_add_f32_dpp v174, v174, v174 row_half_mirror row_mask:0xf bank_mask:0xf bound_ctrl:1
	v_add_f32_dpp v160, v160, v160 row_half_mirror row_mask:0xf bank_mask:0xf bound_ctrl:1
	v_add_f32_dpp v161, v161, v161 row_half_mirror row_mask:0xf bank_mask:0xf bound_ctrl:1
	s_waitcnt lgkmcnt(12)
	v_pk_fma_f32 v[72:73], v[192:193], v[172:173], v[218:219] op_sel_hi:[1,0,1]
	v_pk_fma_f32 v[80:81], v[192:193], v[174:175], v[226:227] op_sel_hi:[1,0,1]
	v_pk_fma_f32 v[74:75], v[194:195], v[172:173], v[220:221] op_sel_hi:[1,0,1]
	v_pk_fma_f32 v[82:83], v[194:195], v[174:175], v[228:229] op_sel_hi:[1,0,1]
	v_pk_fma_f32 v[76:77], v[196:197], v[172:173], v[222:223] op_sel_hi:[1,0,1]
	v_pk_fma_f32 v[84:85], v[196:197], v[174:175], v[230:231] op_sel_hi:[1,0,1]
	v_pk_fma_f32 v[78:79], v[198:199], v[172:173], v[224:225] op_sel_hi:[1,0,1]
	v_pk_fma_f32 v[86:87], v[198:199], v[174:175], v[234:235] op_sel_hi:[1,0,1]
	ds_write_b64 v1, v[160:161] offset:54784
	s_waitcnt lgkmcnt(8)
	v_pk_mul_f32 v[164:165], v[72:73], v[4:5]
	v_pk_mul_f32 v[166:167], v[80:81], v[4:5]
	ds_read_b128 v[48:51], v2 offset:17664
	v_pk_mul_f32 v[168:169], v[72:73], v[208:209]
	v_pk_mul_f32 v[170:171], v[80:81], v[208:209]
	ds_read_b128 v[52:55], v2 offset:17680
	v_pk_fma_f32 v[164:165], v[74:75], v[6:7], v[164:165]
	v_pk_fma_f32 v[166:167], v[82:83], v[6:7], v[166:167]
	ds_read_b128 v[176:179], v2 offset:5632
	v_pk_fma_f32 v[168:169], v[74:75], v[210:211], v[168:169]
	v_pk_fma_f32 v[170:171], v[82:83], v[210:211], v[170:171]
	ds_read_b128 v[180:183], v2 offset:5648
	v_pk_fma_f32 v[164:165], v[76:77], v[8:9], v[164:165]
	v_pk_fma_f32 v[166:167], v[84:85], v[8:9], v[166:167]
	ds_read_b128 v[200:203], v2 offset:13824
	v_pk_fma_f32 v[168:169], v[76:77], v[212:213], v[168:169]
	v_pk_fma_f32 v[170:171], v[84:85], v[212:213], v[170:171]
	ds_read_b128 v[204:207], v2 offset:13840
	v_pk_fma_f32 v[164:165], v[78:79], v[10:11], v[164:165]
	v_pk_fma_f32 v[166:167], v[86:87], v[10:11], v[166:167]
	ds_read_b64 v[216:217], v3 offset:42496
	v_pk_fma_f32 v[168:169], v[78:79], v[214:215], v[168:169]
	v_pk_fma_f32 v[170:171], v[86:87], v[214:215], v[170:171]
	ds_read_b128 v[184:187], v2 offset:1536
	s_waitcnt lgkmcnt(13)
	v_pk_mul_f32 v[218:219], v[26:27], v[40:41] op_sel_hi:[0,1]
	v_pk_mul_f32 v[226:227], v[26:27], v[40:41] op_sel:[1,0]
	ds_read_b128 v[188:191], v2 offset:1552
	v_pk_mul_f32 v[220:221], v[26:27], v[42:43] op_sel_hi:[0,1]
	v_pk_mul_f32 v[228:229], v[26:27], v[42:43] op_sel:[1,0]
	ds_read_b128 v[192:195], v2 offset:9728
	v_pk_mul_f32 v[222:223], v[26:27], v[44:45] op_sel_hi:[0,1]
	v_pk_mul_f32 v[230:231], v[26:27], v[44:45] op_sel:[1,0]
	ds_read_b128 v[196:199], v2 offset:9744
	v_pk_mul_f32 v[224:225], v[26:27], v[46:47] op_sel_hi:[0,1]
	v_pk_mul_f32 v[234:235], v[26:27], v[46:47] op_sel:[1,0]
	v_add_f32_e32 v172, v164, v165
	v_add_f32_e32 v174, v166, v167
	v_add_f32_e32 v160, v168, v169
	v_add_f32_e32 v161, v170, v171
	s_waitcnt lgkmcnt(14)
	v_pk_fma_f32 v[218:219], v[72:73], v[12:13], v[218:219]
	v_pk_fma_f32 v[226:227], v[80:81], v[12:13], v[226:227]
	v_pk_fma_f32 v[220:221], v[74:75], v[14:15], v[220:221]
	v_pk_fma_f32 v[228:229], v[82:83], v[14:15], v[228:229]
	v_add_f32_dpp v172, v172, v172 quad_perm:[1,0,3,2] row_mask:0xf bank_mask:0xf bound_ctrl:1
	v_add_f32_dpp v174, v174, v174 quad_perm:[1,0,3,2] row_mask:0xf bank_mask:0xf bound_ctrl:1
	v_add_f32_dpp v160, v160, v160 quad_perm:[1,0,3,2] row_mask:0xf bank_mask:0xf bound_ctrl:1
	v_add_f32_dpp v161, v161, v161 quad_perm:[1,0,3,2] row_mask:0xf bank_mask:0xf bound_ctrl:1
	v_pk_fma_f32 v[222:223], v[76:77], v[28:29], v[222:223]
	v_pk_fma_f32 v[230:231], v[84:85], v[28:29], v[230:231]
	v_pk_fma_f32 v[224:225], v[78:79], v[30:31], v[224:225]
	v_pk_fma_f32 v[234:235], v[86:87], v[30:31], v[234:235]
	v_add_f32_dpp v172, v172, v172 quad_perm:[2,3,0,1] row_mask:0xf bank_mask:0xf bound_ctrl:1
	v_add_f32_dpp v174, v174, v174 quad_perm:[2,3,0,1] row_mask:0xf bank_mask:0xf bound_ctrl:1
	v_add_f32_dpp v160, v160, v160 quad_perm:[2,3,0,1] row_mask:0xf bank_mask:0xf bound_ctrl:1
	v_add_f32_dpp v161, v161, v161 quad_perm:[2,3,0,1] row_mask:0xf bank_mask:0xf bound_ctrl:1
	v_add_f32_dpp v172, v172, v172 row_half_mirror row_mask:0xf bank_mask:0xf bound_ctrl:1
	v_add_f32_dpp v174, v174, v174 row_half_mirror row_mask:0xf bank_mask:0xf bound_ctrl:1
	v_add_f32_dpp v160, v160, v160 row_half_mirror row_mask:0xf bank_mask:0xf bound_ctrl:1
	v_add_f32_dpp v161, v161, v161 row_half_mirror row_mask:0xf bank_mask:0xf bound_ctrl:1
	s_waitcnt lgkmcnt(12)
	v_pk_fma_f32 v[72:73], v[32:33], v[172:173], v[218:219] op_sel_hi:[1,0,1]
	v_pk_fma_f32 v[80:81], v[32:33], v[174:175], v[226:227] op_sel_hi:[1,0,1]
	v_pk_fma_f32 v[74:75], v[34:35], v[172:173], v[220:221] op_sel_hi:[1,0,1]
	v_pk_fma_f32 v[82:83], v[34:35], v[174:175], v[228:229] op_sel_hi:[1,0,1]
	v_pk_fma_f32 v[76:77], v[36:37], v[172:173], v[222:223] op_sel_hi:[1,0,1]
	v_pk_fma_f32 v[84:85], v[36:37], v[174:175], v[230:231] op_sel_hi:[1,0,1]
	v_pk_fma_f32 v[78:79], v[38:39], v[172:173], v[224:225] op_sel_hi:[1,0,1]
	v_pk_fma_f32 v[86:87], v[38:39], v[174:175], v[234:235] op_sel_hi:[1,0,1]
	ds_write_b64 v1, v[160:161] offset:55040
	s_waitcnt lgkmcnt(8)
	v_pk_mul_f32 v[164:165], v[72:73], v[176:177]
	v_pk_mul_f32 v[166:167], v[80:81], v[176:177]
	ds_read_b128 v[208:211], v2 offset:17920
	v_pk_mul_f32 v[168:169], v[72:73], v[48:49]
	v_pk_mul_f32 v[170:171], v[80:81], v[48:49]
	ds_read_b128 v[212:215], v2 offset:17936
	v_pk_fma_f32 v[164:165], v[74:75], v[178:179], v[164:165]
	v_pk_fma_f32 v[166:167], v[82:83], v[178:179], v[166:167]
	ds_read_b128 v[4:7], v2 offset:5888
	v_pk_fma_f32 v[168:169], v[74:75], v[50:51], v[168:169]
	v_pk_fma_f32 v[170:171], v[82:83], v[50:51], v[170:171]
	ds_read_b128 v[8:11], v2 offset:5904
	v_pk_fma_f32 v[164:165], v[76:77], v[180:181], v[164:165]
	v_pk_fma_f32 v[166:167], v[84:85], v[180:181], v[166:167]
	ds_read_b128 v[40:43], v2 offset:14080
	v_pk_fma_f32 v[168:169], v[76:77], v[52:53], v[168:169]
	v_pk_fma_f32 v[170:171], v[84:85], v[52:53], v[170:171]
	ds_read_b128 v[44:47], v2 offset:14096
	v_pk_fma_f32 v[164:165], v[78:79], v[182:183], v[164:165]
	v_pk_fma_f32 v[166:167], v[86:87], v[182:183], v[166:167]
	ds_read_b64 v[26:27], v3 offset:42752
	v_pk_fma_f32 v[168:169], v[78:79], v[54:55], v[168:169]
	v_pk_fma_f32 v[170:171], v[86:87], v[54:55], v[170:171]
	ds_read_b128 v[12:15], v2 offset:1792
	s_waitcnt lgkmcnt(13)
	v_pk_mul_f32 v[218:219], v[216:217], v[200:201] op_sel_hi:[0,1]
	v_pk_mul_f32 v[226:227], v[216:217], v[200:201] op_sel:[1,0]
	ds_read_b128 v[28:31], v2 offset:1808
	v_pk_mul_f32 v[220:221], v[216:217], v[202:203] op_sel_hi:[0,1]
	v_pk_mul_f32 v[228:229], v[216:217], v[202:203] op_sel:[1,0]
	ds_read_b128 v[32:35], v2 offset:9984
	v_pk_mul_f32 v[222:223], v[216:217], v[204:205] op_sel_hi:[0,1]
	v_pk_mul_f32 v[230:231], v[216:217], v[204:205] op_sel:[1,0]
	ds_read_b128 v[36:39], v2 offset:10000
	v_pk_mul_f32 v[224:225], v[216:217], v[206:207] op_sel_hi:[0,1]
	v_pk_mul_f32 v[234:235], v[216:217], v[206:207] op_sel:[1,0]
	v_add_f32_e32 v172, v164, v165
	v_add_f32_e32 v174, v166, v167
	v_add_f32_e32 v160, v168, v169
	v_add_f32_e32 v161, v170, v171
	s_waitcnt lgkmcnt(14)
	v_pk_fma_f32 v[218:219], v[72:73], v[184:185], v[218:219]
	v_pk_fma_f32 v[226:227], v[80:81], v[184:185], v[226:227]
	v_pk_fma_f32 v[220:221], v[74:75], v[186:187], v[220:221]
	v_pk_fma_f32 v[228:229], v[82:83], v[186:187], v[228:229]
	v_add_f32_dpp v172, v172, v172 quad_perm:[1,0,3,2] row_mask:0xf bank_mask:0xf bound_ctrl:1
	v_add_f32_dpp v174, v174, v174 quad_perm:[1,0,3,2] row_mask:0xf bank_mask:0xf bound_ctrl:1
	v_add_f32_dpp v160, v160, v160 quad_perm:[1,0,3,2] row_mask:0xf bank_mask:0xf bound_ctrl:1
	v_add_f32_dpp v161, v161, v161 quad_perm:[1,0,3,2] row_mask:0xf bank_mask:0xf bound_ctrl:1
	v_pk_fma_f32 v[222:223], v[76:77], v[188:189], v[222:223]
	v_pk_fma_f32 v[230:231], v[84:85], v[188:189], v[230:231]
	v_pk_fma_f32 v[224:225], v[78:79], v[190:191], v[224:225]
	v_pk_fma_f32 v[234:235], v[86:87], v[190:191], v[234:235]
	v_add_f32_dpp v172, v172, v172 quad_perm:[2,3,0,1] row_mask:0xf bank_mask:0xf bound_ctrl:1
	v_add_f32_dpp v174, v174, v174 quad_perm:[2,3,0,1] row_mask:0xf bank_mask:0xf bound_ctrl:1
	v_add_f32_dpp v160, v160, v160 quad_perm:[2,3,0,1] row_mask:0xf bank_mask:0xf bound_ctrl:1
	v_add_f32_dpp v161, v161, v161 quad_perm:[2,3,0,1] row_mask:0xf bank_mask:0xf bound_ctrl:1
	v_add_f32_dpp v172, v172, v172 row_half_mirror row_mask:0xf bank_mask:0xf bound_ctrl:1
	v_add_f32_dpp v174, v174, v174 row_half_mirror row_mask:0xf bank_mask:0xf bound_ctrl:1
	v_add_f32_dpp v160, v160, v160 row_half_mirror row_mask:0xf bank_mask:0xf bound_ctrl:1
	v_add_f32_dpp v161, v161, v161 row_half_mirror row_mask:0xf bank_mask:0xf bound_ctrl:1
	s_waitcnt lgkmcnt(12)
	v_pk_fma_f32 v[72:73], v[192:193], v[172:173], v[218:219] op_sel_hi:[1,0,1]
	v_pk_fma_f32 v[80:81], v[192:193], v[174:175], v[226:227] op_sel_hi:[1,0,1]
	v_pk_fma_f32 v[74:75], v[194:195], v[172:173], v[220:221] op_sel_hi:[1,0,1]
	v_pk_fma_f32 v[82:83], v[194:195], v[174:175], v[228:229] op_sel_hi:[1,0,1]
	v_pk_fma_f32 v[76:77], v[196:197], v[172:173], v[222:223] op_sel_hi:[1,0,1]
	v_pk_fma_f32 v[84:85], v[196:197], v[174:175], v[230:231] op_sel_hi:[1,0,1]
	v_pk_fma_f32 v[78:79], v[198:199], v[172:173], v[224:225] op_sel_hi:[1,0,1]
	v_pk_fma_f32 v[86:87], v[198:199], v[174:175], v[234:235] op_sel_hi:[1,0,1]
	ds_write_b64 v1, v[160:161] offset:55296
	s_waitcnt lgkmcnt(8)
	v_pk_mul_f32 v[164:165], v[72:73], v[4:5]
	v_pk_mul_f32 v[166:167], v[80:81], v[4:5]
	ds_read_b128 v[48:51], v2 offset:18176
	v_pk_mul_f32 v[168:169], v[72:73], v[208:209]
	v_pk_mul_f32 v[170:171], v[80:81], v[208:209]
	ds_read_b128 v[52:55], v2 offset:18192
	v_pk_fma_f32 v[164:165], v[74:75], v[6:7], v[164:165]
	v_pk_fma_f32 v[166:167], v[82:83], v[6:7], v[166:167]
	ds_read_b128 v[176:179], v2 offset:6144
	v_pk_fma_f32 v[168:169], v[74:75], v[210:211], v[168:169]
	v_pk_fma_f32 v[170:171], v[82:83], v[210:211], v[170:171]
	ds_read_b128 v[180:183], v2 offset:6160
	v_pk_fma_f32 v[164:165], v[76:77], v[8:9], v[164:165]
	v_pk_fma_f32 v[166:167], v[84:85], v[8:9], v[166:167]
	ds_read_b128 v[200:203], v2 offset:14336
	v_pk_fma_f32 v[168:169], v[76:77], v[212:213], v[168:169]
	v_pk_fma_f32 v[170:171], v[84:85], v[212:213], v[170:171]
	ds_read_b128 v[204:207], v2 offset:14352
	v_pk_fma_f32 v[164:165], v[78:79], v[10:11], v[164:165]
	v_pk_fma_f32 v[166:167], v[86:87], v[10:11], v[166:167]
	ds_read_b64 v[216:217], v3 offset:43008
	v_pk_fma_f32 v[168:169], v[78:79], v[214:215], v[168:169]
	v_pk_fma_f32 v[170:171], v[86:87], v[214:215], v[170:171]
	ds_read_b128 v[184:187], v2 offset:2048
	s_waitcnt lgkmcnt(13)
	v_pk_mul_f32 v[218:219], v[26:27], v[40:41] op_sel_hi:[0,1]
	v_pk_mul_f32 v[226:227], v[26:27], v[40:41] op_sel:[1,0]
	ds_read_b128 v[188:191], v2 offset:2064
	v_pk_mul_f32 v[220:221], v[26:27], v[42:43] op_sel_hi:[0,1]
	v_pk_mul_f32 v[228:229], v[26:27], v[42:43] op_sel:[1,0]
	ds_read_b128 v[192:195], v2 offset:10240
	v_pk_mul_f32 v[222:223], v[26:27], v[44:45] op_sel_hi:[0,1]
	v_pk_mul_f32 v[230:231], v[26:27], v[44:45] op_sel:[1,0]
	ds_read_b128 v[196:199], v2 offset:10256
	v_pk_mul_f32 v[224:225], v[26:27], v[46:47] op_sel_hi:[0,1]
	v_pk_mul_f32 v[234:235], v[26:27], v[46:47] op_sel:[1,0]
	v_add_f32_e32 v172, v164, v165
	v_add_f32_e32 v174, v166, v167
	v_add_f32_e32 v160, v168, v169
	v_add_f32_e32 v161, v170, v171
	s_waitcnt lgkmcnt(14)
	v_pk_fma_f32 v[218:219], v[72:73], v[12:13], v[218:219]
	v_pk_fma_f32 v[226:227], v[80:81], v[12:13], v[226:227]
	v_pk_fma_f32 v[220:221], v[74:75], v[14:15], v[220:221]
	v_pk_fma_f32 v[228:229], v[82:83], v[14:15], v[228:229]
	v_add_f32_dpp v172, v172, v172 quad_perm:[1,0,3,2] row_mask:0xf bank_mask:0xf bound_ctrl:1
	v_add_f32_dpp v174, v174, v174 quad_perm:[1,0,3,2] row_mask:0xf bank_mask:0xf bound_ctrl:1
	v_add_f32_dpp v160, v160, v160 quad_perm:[1,0,3,2] row_mask:0xf bank_mask:0xf bound_ctrl:1
	v_add_f32_dpp v161, v161, v161 quad_perm:[1,0,3,2] row_mask:0xf bank_mask:0xf bound_ctrl:1
	v_pk_fma_f32 v[222:223], v[76:77], v[28:29], v[222:223]
	v_pk_fma_f32 v[230:231], v[84:85], v[28:29], v[230:231]
	v_pk_fma_f32 v[224:225], v[78:79], v[30:31], v[224:225]
	v_pk_fma_f32 v[234:235], v[86:87], v[30:31], v[234:235]
	v_add_f32_dpp v172, v172, v172 quad_perm:[2,3,0,1] row_mask:0xf bank_mask:0xf bound_ctrl:1
	v_add_f32_dpp v174, v174, v174 quad_perm:[2,3,0,1] row_mask:0xf bank_mask:0xf bound_ctrl:1
	v_add_f32_dpp v160, v160, v160 quad_perm:[2,3,0,1] row_mask:0xf bank_mask:0xf bound_ctrl:1
	v_add_f32_dpp v161, v161, v161 quad_perm:[2,3,0,1] row_mask:0xf bank_mask:0xf bound_ctrl:1
	v_add_f32_dpp v172, v172, v172 row_half_mirror row_mask:0xf bank_mask:0xf bound_ctrl:1
	v_add_f32_dpp v174, v174, v174 row_half_mirror row_mask:0xf bank_mask:0xf bound_ctrl:1
	v_add_f32_dpp v160, v160, v160 row_half_mirror row_mask:0xf bank_mask:0xf bound_ctrl:1
	v_add_f32_dpp v161, v161, v161 row_half_mirror row_mask:0xf bank_mask:0xf bound_ctrl:1
	s_waitcnt lgkmcnt(12)
	v_pk_fma_f32 v[72:73], v[32:33], v[172:173], v[218:219] op_sel_hi:[1,0,1]
	v_pk_fma_f32 v[80:81], v[32:33], v[174:175], v[226:227] op_sel_hi:[1,0,1]
	v_pk_fma_f32 v[74:75], v[34:35], v[172:173], v[220:221] op_sel_hi:[1,0,1]
	v_pk_fma_f32 v[82:83], v[34:35], v[174:175], v[228:229] op_sel_hi:[1,0,1]
	v_pk_fma_f32 v[76:77], v[36:37], v[172:173], v[222:223] op_sel_hi:[1,0,1]
	v_pk_fma_f32 v[84:85], v[36:37], v[174:175], v[230:231] op_sel_hi:[1,0,1]
	v_pk_fma_f32 v[78:79], v[38:39], v[172:173], v[224:225] op_sel_hi:[1,0,1]
	v_pk_fma_f32 v[86:87], v[38:39], v[174:175], v[234:235] op_sel_hi:[1,0,1]
	ds_write_b64 v1, v[160:161] offset:55552
	s_waitcnt lgkmcnt(8)
	v_pk_mul_f32 v[164:165], v[72:73], v[176:177]
	v_pk_mul_f32 v[166:167], v[80:81], v[176:177]
	ds_read_b128 v[208:211], v2 offset:18432
	v_pk_mul_f32 v[168:169], v[72:73], v[48:49]
	v_pk_mul_f32 v[170:171], v[80:81], v[48:49]
	ds_read_b128 v[212:215], v2 offset:18448
	v_pk_fma_f32 v[164:165], v[74:75], v[178:179], v[164:165]
	v_pk_fma_f32 v[166:167], v[82:83], v[178:179], v[166:167]
	ds_read_b128 v[4:7], v2 offset:6400
	v_pk_fma_f32 v[168:169], v[74:75], v[50:51], v[168:169]
	v_pk_fma_f32 v[170:171], v[82:83], v[50:51], v[170:171]
	ds_read_b128 v[8:11], v2 offset:6416
	v_pk_fma_f32 v[164:165], v[76:77], v[180:181], v[164:165]
	v_pk_fma_f32 v[166:167], v[84:85], v[180:181], v[166:167]
	ds_read_b128 v[40:43], v2 offset:14592
	v_pk_fma_f32 v[168:169], v[76:77], v[52:53], v[168:169]
	v_pk_fma_f32 v[170:171], v[84:85], v[52:53], v[170:171]
	ds_read_b128 v[44:47], v2 offset:14608
	v_pk_fma_f32 v[164:165], v[78:79], v[182:183], v[164:165]
	v_pk_fma_f32 v[166:167], v[86:87], v[182:183], v[166:167]
	ds_read_b64 v[26:27], v3 offset:43264
	v_pk_fma_f32 v[168:169], v[78:79], v[54:55], v[168:169]
	v_pk_fma_f32 v[170:171], v[86:87], v[54:55], v[170:171]
	ds_read_b128 v[12:15], v2 offset:2304
	s_waitcnt lgkmcnt(13)
	v_pk_mul_f32 v[218:219], v[216:217], v[200:201] op_sel_hi:[0,1]
	v_pk_mul_f32 v[226:227], v[216:217], v[200:201] op_sel:[1,0]
	ds_read_b128 v[28:31], v2 offset:2320
	v_pk_mul_f32 v[220:221], v[216:217], v[202:203] op_sel_hi:[0,1]
	v_pk_mul_f32 v[228:229], v[216:217], v[202:203] op_sel:[1,0]
	ds_read_b128 v[32:35], v2 offset:10496
	v_pk_mul_f32 v[222:223], v[216:217], v[204:205] op_sel_hi:[0,1]
	v_pk_mul_f32 v[230:231], v[216:217], v[204:205] op_sel:[1,0]
	ds_read_b128 v[36:39], v2 offset:10512
	v_pk_mul_f32 v[224:225], v[216:217], v[206:207] op_sel_hi:[0,1]
	v_pk_mul_f32 v[234:235], v[216:217], v[206:207] op_sel:[1,0]
	v_add_f32_e32 v172, v164, v165
	v_add_f32_e32 v174, v166, v167
	v_add_f32_e32 v160, v168, v169
	v_add_f32_e32 v161, v170, v171
	s_waitcnt lgkmcnt(14)
	v_pk_fma_f32 v[218:219], v[72:73], v[184:185], v[218:219]
	v_pk_fma_f32 v[226:227], v[80:81], v[184:185], v[226:227]
	v_pk_fma_f32 v[220:221], v[74:75], v[186:187], v[220:221]
	v_pk_fma_f32 v[228:229], v[82:83], v[186:187], v[228:229]
	v_add_f32_dpp v172, v172, v172 quad_perm:[1,0,3,2] row_mask:0xf bank_mask:0xf bound_ctrl:1
	v_add_f32_dpp v174, v174, v174 quad_perm:[1,0,3,2] row_mask:0xf bank_mask:0xf bound_ctrl:1
	v_add_f32_dpp v160, v160, v160 quad_perm:[1,0,3,2] row_mask:0xf bank_mask:0xf bound_ctrl:1
	v_add_f32_dpp v161, v161, v161 quad_perm:[1,0,3,2] row_mask:0xf bank_mask:0xf bound_ctrl:1
	v_pk_fma_f32 v[222:223], v[76:77], v[188:189], v[222:223]
	v_pk_fma_f32 v[230:231], v[84:85], v[188:189], v[230:231]
	v_pk_fma_f32 v[224:225], v[78:79], v[190:191], v[224:225]
	v_pk_fma_f32 v[234:235], v[86:87], v[190:191], v[234:235]
	v_add_f32_dpp v172, v172, v172 quad_perm:[2,3,0,1] row_mask:0xf bank_mask:0xf bound_ctrl:1
	v_add_f32_dpp v174, v174, v174 quad_perm:[2,3,0,1] row_mask:0xf bank_mask:0xf bound_ctrl:1
	v_add_f32_dpp v160, v160, v160 quad_perm:[2,3,0,1] row_mask:0xf bank_mask:0xf bound_ctrl:1
	v_add_f32_dpp v161, v161, v161 quad_perm:[2,3,0,1] row_mask:0xf bank_mask:0xf bound_ctrl:1
	v_add_f32_dpp v172, v172, v172 row_half_mirror row_mask:0xf bank_mask:0xf bound_ctrl:1
	v_add_f32_dpp v174, v174, v174 row_half_mirror row_mask:0xf bank_mask:0xf bound_ctrl:1
	v_add_f32_dpp v160, v160, v160 row_half_mirror row_mask:0xf bank_mask:0xf bound_ctrl:1
	v_add_f32_dpp v161, v161, v161 row_half_mirror row_mask:0xf bank_mask:0xf bound_ctrl:1
	s_waitcnt lgkmcnt(12)
	v_pk_fma_f32 v[72:73], v[192:193], v[172:173], v[218:219] op_sel_hi:[1,0,1]
	v_pk_fma_f32 v[80:81], v[192:193], v[174:175], v[226:227] op_sel_hi:[1,0,1]
	v_pk_fma_f32 v[74:75], v[194:195], v[172:173], v[220:221] op_sel_hi:[1,0,1]
	v_pk_fma_f32 v[82:83], v[194:195], v[174:175], v[228:229] op_sel_hi:[1,0,1]
	v_pk_fma_f32 v[76:77], v[196:197], v[172:173], v[222:223] op_sel_hi:[1,0,1]
	v_pk_fma_f32 v[84:85], v[196:197], v[174:175], v[230:231] op_sel_hi:[1,0,1]
	v_pk_fma_f32 v[78:79], v[198:199], v[172:173], v[224:225] op_sel_hi:[1,0,1]
	v_pk_fma_f32 v[86:87], v[198:199], v[174:175], v[234:235] op_sel_hi:[1,0,1]
	ds_write_b64 v1, v[160:161] offset:55808
	s_waitcnt lgkmcnt(8)
	v_pk_mul_f32 v[164:165], v[72:73], v[4:5]
	v_pk_mul_f32 v[166:167], v[80:81], v[4:5]
	ds_read_b128 v[48:51], v2 offset:18688
	v_pk_mul_f32 v[168:169], v[72:73], v[208:209]
	v_pk_mul_f32 v[170:171], v[80:81], v[208:209]
	ds_read_b128 v[52:55], v2 offset:18704
	v_pk_fma_f32 v[164:165], v[74:75], v[6:7], v[164:165]
	v_pk_fma_f32 v[166:167], v[82:83], v[6:7], v[166:167]
	ds_read_b128 v[176:179], v2 offset:6656
	v_pk_fma_f32 v[168:169], v[74:75], v[210:211], v[168:169]
	v_pk_fma_f32 v[170:171], v[82:83], v[210:211], v[170:171]
	ds_read_b128 v[180:183], v2 offset:6672
	v_pk_fma_f32 v[164:165], v[76:77], v[8:9], v[164:165]
	v_pk_fma_f32 v[166:167], v[84:85], v[8:9], v[166:167]
	ds_read_b128 v[200:203], v2 offset:14848
	v_pk_fma_f32 v[168:169], v[76:77], v[212:213], v[168:169]
	v_pk_fma_f32 v[170:171], v[84:85], v[212:213], v[170:171]
	ds_read_b128 v[204:207], v2 offset:14864
	v_pk_fma_f32 v[164:165], v[78:79], v[10:11], v[164:165]
	v_pk_fma_f32 v[166:167], v[86:87], v[10:11], v[166:167]
	ds_read_b64 v[216:217], v3 offset:43520
	v_pk_fma_f32 v[168:169], v[78:79], v[214:215], v[168:169]
	v_pk_fma_f32 v[170:171], v[86:87], v[214:215], v[170:171]
	ds_read_b128 v[184:187], v2 offset:2560
	s_waitcnt lgkmcnt(13)
	v_pk_mul_f32 v[218:219], v[26:27], v[40:41] op_sel_hi:[0,1]
	v_pk_mul_f32 v[226:227], v[26:27], v[40:41] op_sel:[1,0]
	ds_read_b128 v[188:191], v2 offset:2576
	v_pk_mul_f32 v[220:221], v[26:27], v[42:43] op_sel_hi:[0,1]
	v_pk_mul_f32 v[228:229], v[26:27], v[42:43] op_sel:[1,0]
	ds_read_b128 v[192:195], v2 offset:10752
	v_pk_mul_f32 v[222:223], v[26:27], v[44:45] op_sel_hi:[0,1]
	v_pk_mul_f32 v[230:231], v[26:27], v[44:45] op_sel:[1,0]
	ds_read_b128 v[196:199], v2 offset:10768
	v_pk_mul_f32 v[224:225], v[26:27], v[46:47] op_sel_hi:[0,1]
	v_pk_mul_f32 v[234:235], v[26:27], v[46:47] op_sel:[1,0]
	v_add_f32_e32 v172, v164, v165
	v_add_f32_e32 v174, v166, v167
	v_add_f32_e32 v160, v168, v169
	v_add_f32_e32 v161, v170, v171
	s_waitcnt lgkmcnt(14)
	v_pk_fma_f32 v[218:219], v[72:73], v[12:13], v[218:219]
	v_pk_fma_f32 v[226:227], v[80:81], v[12:13], v[226:227]
	v_pk_fma_f32 v[220:221], v[74:75], v[14:15], v[220:221]
	v_pk_fma_f32 v[228:229], v[82:83], v[14:15], v[228:229]
	v_add_f32_dpp v172, v172, v172 quad_perm:[1,0,3,2] row_mask:0xf bank_mask:0xf bound_ctrl:1
	v_add_f32_dpp v174, v174, v174 quad_perm:[1,0,3,2] row_mask:0xf bank_mask:0xf bound_ctrl:1
	v_add_f32_dpp v160, v160, v160 quad_perm:[1,0,3,2] row_mask:0xf bank_mask:0xf bound_ctrl:1
	v_add_f32_dpp v161, v161, v161 quad_perm:[1,0,3,2] row_mask:0xf bank_mask:0xf bound_ctrl:1
	v_pk_fma_f32 v[222:223], v[76:77], v[28:29], v[222:223]
	v_pk_fma_f32 v[230:231], v[84:85], v[28:29], v[230:231]
	v_pk_fma_f32 v[224:225], v[78:79], v[30:31], v[224:225]
	v_pk_fma_f32 v[234:235], v[86:87], v[30:31], v[234:235]
	v_add_f32_dpp v172, v172, v172 quad_perm:[2,3,0,1] row_mask:0xf bank_mask:0xf bound_ctrl:1
	v_add_f32_dpp v174, v174, v174 quad_perm:[2,3,0,1] row_mask:0xf bank_mask:0xf bound_ctrl:1
	v_add_f32_dpp v160, v160, v160 quad_perm:[2,3,0,1] row_mask:0xf bank_mask:0xf bound_ctrl:1
	v_add_f32_dpp v161, v161, v161 quad_perm:[2,3,0,1] row_mask:0xf bank_mask:0xf bound_ctrl:1
	v_add_f32_dpp v172, v172, v172 row_half_mirror row_mask:0xf bank_mask:0xf bound_ctrl:1
	v_add_f32_dpp v174, v174, v174 row_half_mirror row_mask:0xf bank_mask:0xf bound_ctrl:1
	v_add_f32_dpp v160, v160, v160 row_half_mirror row_mask:0xf bank_mask:0xf bound_ctrl:1
	v_add_f32_dpp v161, v161, v161 row_half_mirror row_mask:0xf bank_mask:0xf bound_ctrl:1
	s_waitcnt lgkmcnt(12)
	v_pk_fma_f32 v[72:73], v[32:33], v[172:173], v[218:219] op_sel_hi:[1,0,1]
	v_pk_fma_f32 v[80:81], v[32:33], v[174:175], v[226:227] op_sel_hi:[1,0,1]
	v_pk_fma_f32 v[74:75], v[34:35], v[172:173], v[220:221] op_sel_hi:[1,0,1]
	v_pk_fma_f32 v[82:83], v[34:35], v[174:175], v[228:229] op_sel_hi:[1,0,1]
	v_pk_fma_f32 v[76:77], v[36:37], v[172:173], v[222:223] op_sel_hi:[1,0,1]
	v_pk_fma_f32 v[84:85], v[36:37], v[174:175], v[230:231] op_sel_hi:[1,0,1]
	v_pk_fma_f32 v[78:79], v[38:39], v[172:173], v[224:225] op_sel_hi:[1,0,1]
	v_pk_fma_f32 v[86:87], v[38:39], v[174:175], v[234:235] op_sel_hi:[1,0,1]
	ds_write_b64 v1, v[160:161] offset:56064
	s_waitcnt lgkmcnt(8)
	v_pk_mul_f32 v[164:165], v[72:73], v[176:177]
	v_pk_mul_f32 v[166:167], v[80:81], v[176:177]
	ds_read_b128 v[208:211], v2 offset:18944
	v_pk_mul_f32 v[168:169], v[72:73], v[48:49]
	v_pk_mul_f32 v[170:171], v[80:81], v[48:49]
	ds_read_b128 v[212:215], v2 offset:18960
	v_pk_fma_f32 v[164:165], v[74:75], v[178:179], v[164:165]
	v_pk_fma_f32 v[166:167], v[82:83], v[178:179], v[166:167]
	ds_read_b128 v[4:7], v2 offset:6912
	v_pk_fma_f32 v[168:169], v[74:75], v[50:51], v[168:169]
	v_pk_fma_f32 v[170:171], v[82:83], v[50:51], v[170:171]
	ds_read_b128 v[8:11], v2 offset:6928
	v_pk_fma_f32 v[164:165], v[76:77], v[180:181], v[164:165]
	v_pk_fma_f32 v[166:167], v[84:85], v[180:181], v[166:167]
	ds_read_b128 v[40:43], v2 offset:15104
	v_pk_fma_f32 v[168:169], v[76:77], v[52:53], v[168:169]
	v_pk_fma_f32 v[170:171], v[84:85], v[52:53], v[170:171]
	ds_read_b128 v[44:47], v2 offset:15120
	v_pk_fma_f32 v[164:165], v[78:79], v[182:183], v[164:165]
	v_pk_fma_f32 v[166:167], v[86:87], v[182:183], v[166:167]
	ds_read_b64 v[26:27], v3 offset:43776
	v_pk_fma_f32 v[168:169], v[78:79], v[54:55], v[168:169]
	v_pk_fma_f32 v[170:171], v[86:87], v[54:55], v[170:171]
	ds_read_b128 v[12:15], v2 offset:2816
	s_waitcnt lgkmcnt(13)
	v_pk_mul_f32 v[218:219], v[216:217], v[200:201] op_sel_hi:[0,1]
	v_pk_mul_f32 v[226:227], v[216:217], v[200:201] op_sel:[1,0]
	ds_read_b128 v[28:31], v2 offset:2832
	v_pk_mul_f32 v[220:221], v[216:217], v[202:203] op_sel_hi:[0,1]
	v_pk_mul_f32 v[228:229], v[216:217], v[202:203] op_sel:[1,0]
	ds_read_b128 v[32:35], v2 offset:11008
	v_pk_mul_f32 v[222:223], v[216:217], v[204:205] op_sel_hi:[0,1]
	v_pk_mul_f32 v[230:231], v[216:217], v[204:205] op_sel:[1,0]
	ds_read_b128 v[36:39], v2 offset:11024
	v_pk_mul_f32 v[224:225], v[216:217], v[206:207] op_sel_hi:[0,1]
	v_pk_mul_f32 v[234:235], v[216:217], v[206:207] op_sel:[1,0]
	v_add_f32_e32 v172, v164, v165
	v_add_f32_e32 v174, v166, v167
	v_add_f32_e32 v160, v168, v169
	v_add_f32_e32 v161, v170, v171
	s_waitcnt lgkmcnt(14)
	v_pk_fma_f32 v[218:219], v[72:73], v[184:185], v[218:219]
	v_pk_fma_f32 v[226:227], v[80:81], v[184:185], v[226:227]
	v_pk_fma_f32 v[220:221], v[74:75], v[186:187], v[220:221]
	v_pk_fma_f32 v[228:229], v[82:83], v[186:187], v[228:229]
	v_add_f32_dpp v172, v172, v172 quad_perm:[1,0,3,2] row_mask:0xf bank_mask:0xf bound_ctrl:1
	v_add_f32_dpp v174, v174, v174 quad_perm:[1,0,3,2] row_mask:0xf bank_mask:0xf bound_ctrl:1
	v_add_f32_dpp v160, v160, v160 quad_perm:[1,0,3,2] row_mask:0xf bank_mask:0xf bound_ctrl:1
	v_add_f32_dpp v161, v161, v161 quad_perm:[1,0,3,2] row_mask:0xf bank_mask:0xf bound_ctrl:1
	v_pk_fma_f32 v[222:223], v[76:77], v[188:189], v[222:223]
	v_pk_fma_f32 v[230:231], v[84:85], v[188:189], v[230:231]
	v_pk_fma_f32 v[224:225], v[78:79], v[190:191], v[224:225]
	v_pk_fma_f32 v[234:235], v[86:87], v[190:191], v[234:235]
	v_add_f32_dpp v172, v172, v172 quad_perm:[2,3,0,1] row_mask:0xf bank_mask:0xf bound_ctrl:1
	v_add_f32_dpp v174, v174, v174 quad_perm:[2,3,0,1] row_mask:0xf bank_mask:0xf bound_ctrl:1
	v_add_f32_dpp v160, v160, v160 quad_perm:[2,3,0,1] row_mask:0xf bank_mask:0xf bound_ctrl:1
	v_add_f32_dpp v161, v161, v161 quad_perm:[2,3,0,1] row_mask:0xf bank_mask:0xf bound_ctrl:1
	v_add_f32_dpp v172, v172, v172 row_half_mirror row_mask:0xf bank_mask:0xf bound_ctrl:1
	v_add_f32_dpp v174, v174, v174 row_half_mirror row_mask:0xf bank_mask:0xf bound_ctrl:1
	v_add_f32_dpp v160, v160, v160 row_half_mirror row_mask:0xf bank_mask:0xf bound_ctrl:1
	v_add_f32_dpp v161, v161, v161 row_half_mirror row_mask:0xf bank_mask:0xf bound_ctrl:1
	s_waitcnt lgkmcnt(12)
	v_pk_fma_f32 v[72:73], v[192:193], v[172:173], v[218:219] op_sel_hi:[1,0,1]
	v_pk_fma_f32 v[80:81], v[192:193], v[174:175], v[226:227] op_sel_hi:[1,0,1]
	v_pk_fma_f32 v[74:75], v[194:195], v[172:173], v[220:221] op_sel_hi:[1,0,1]
	v_pk_fma_f32 v[82:83], v[194:195], v[174:175], v[228:229] op_sel_hi:[1,0,1]
	v_pk_fma_f32 v[76:77], v[196:197], v[172:173], v[222:223] op_sel_hi:[1,0,1]
	v_pk_fma_f32 v[84:85], v[196:197], v[174:175], v[230:231] op_sel_hi:[1,0,1]
	v_pk_fma_f32 v[78:79], v[198:199], v[172:173], v[224:225] op_sel_hi:[1,0,1]
	v_pk_fma_f32 v[86:87], v[198:199], v[174:175], v[234:235] op_sel_hi:[1,0,1]
	ds_write_b64 v1, v[160:161] offset:56320
	s_waitcnt lgkmcnt(8)
	v_pk_mul_f32 v[164:165], v[72:73], v[4:5]
	v_pk_mul_f32 v[166:167], v[80:81], v[4:5]
	ds_read_b128 v[48:51], v2 offset:19200
	v_pk_mul_f32 v[168:169], v[72:73], v[208:209]
	v_pk_mul_f32 v[170:171], v[80:81], v[208:209]
	ds_read_b128 v[52:55], v2 offset:19216
	v_pk_fma_f32 v[164:165], v[74:75], v[6:7], v[164:165]
	v_pk_fma_f32 v[166:167], v[82:83], v[6:7], v[166:167]
	ds_read_b128 v[176:179], v2 offset:7168
	v_pk_fma_f32 v[168:169], v[74:75], v[210:211], v[168:169]
	v_pk_fma_f32 v[170:171], v[82:83], v[210:211], v[170:171]
	ds_read_b128 v[180:183], v2 offset:7184
	v_pk_fma_f32 v[164:165], v[76:77], v[8:9], v[164:165]
	v_pk_fma_f32 v[166:167], v[84:85], v[8:9], v[166:167]
	ds_read_b128 v[200:203], v2 offset:15360
	v_pk_fma_f32 v[168:169], v[76:77], v[212:213], v[168:169]
	v_pk_fma_f32 v[170:171], v[84:85], v[212:213], v[170:171]
	ds_read_b128 v[204:207], v2 offset:15376
	v_pk_fma_f32 v[164:165], v[78:79], v[10:11], v[164:165]
	v_pk_fma_f32 v[166:167], v[86:87], v[10:11], v[166:167]
	ds_read_b64 v[216:217], v3 offset:44032
	v_pk_fma_f32 v[168:169], v[78:79], v[214:215], v[168:169]
	v_pk_fma_f32 v[170:171], v[86:87], v[214:215], v[170:171]
	ds_read_b128 v[184:187], v2 offset:3072
	s_waitcnt lgkmcnt(13)
	v_pk_mul_f32 v[218:219], v[26:27], v[40:41] op_sel_hi:[0,1]
	v_pk_mul_f32 v[226:227], v[26:27], v[40:41] op_sel:[1,0]
	ds_read_b128 v[188:191], v2 offset:3088
	v_pk_mul_f32 v[220:221], v[26:27], v[42:43] op_sel_hi:[0,1]
	v_pk_mul_f32 v[228:229], v[26:27], v[42:43] op_sel:[1,0]
	ds_read_b128 v[192:195], v2 offset:11264
	v_pk_mul_f32 v[222:223], v[26:27], v[44:45] op_sel_hi:[0,1]
	v_pk_mul_f32 v[230:231], v[26:27], v[44:45] op_sel:[1,0]
	ds_read_b128 v[196:199], v2 offset:11280
	v_pk_mul_f32 v[224:225], v[26:27], v[46:47] op_sel_hi:[0,1]
	v_pk_mul_f32 v[234:235], v[26:27], v[46:47] op_sel:[1,0]
	v_add_f32_e32 v172, v164, v165
	v_add_f32_e32 v174, v166, v167
	v_add_f32_e32 v160, v168, v169
	v_add_f32_e32 v161, v170, v171
	s_waitcnt lgkmcnt(14)
	v_pk_fma_f32 v[218:219], v[72:73], v[12:13], v[218:219]
	v_pk_fma_f32 v[226:227], v[80:81], v[12:13], v[226:227]
	v_pk_fma_f32 v[220:221], v[74:75], v[14:15], v[220:221]
	v_pk_fma_f32 v[228:229], v[82:83], v[14:15], v[228:229]
	v_add_f32_dpp v172, v172, v172 quad_perm:[1,0,3,2] row_mask:0xf bank_mask:0xf bound_ctrl:1
	v_add_f32_dpp v174, v174, v174 quad_perm:[1,0,3,2] row_mask:0xf bank_mask:0xf bound_ctrl:1
	v_add_f32_dpp v160, v160, v160 quad_perm:[1,0,3,2] row_mask:0xf bank_mask:0xf bound_ctrl:1
	v_add_f32_dpp v161, v161, v161 quad_perm:[1,0,3,2] row_mask:0xf bank_mask:0xf bound_ctrl:1
	v_pk_fma_f32 v[222:223], v[76:77], v[28:29], v[222:223]
	v_pk_fma_f32 v[230:231], v[84:85], v[28:29], v[230:231]
	v_pk_fma_f32 v[224:225], v[78:79], v[30:31], v[224:225]
	v_pk_fma_f32 v[234:235], v[86:87], v[30:31], v[234:235]
	v_add_f32_dpp v172, v172, v172 quad_perm:[2,3,0,1] row_mask:0xf bank_mask:0xf bound_ctrl:1
	v_add_f32_dpp v174, v174, v174 quad_perm:[2,3,0,1] row_mask:0xf bank_mask:0xf bound_ctrl:1
	v_add_f32_dpp v160, v160, v160 quad_perm:[2,3,0,1] row_mask:0xf bank_mask:0xf bound_ctrl:1
	v_add_f32_dpp v161, v161, v161 quad_perm:[2,3,0,1] row_mask:0xf bank_mask:0xf bound_ctrl:1
	v_add_f32_dpp v172, v172, v172 row_half_mirror row_mask:0xf bank_mask:0xf bound_ctrl:1
	v_add_f32_dpp v174, v174, v174 row_half_mirror row_mask:0xf bank_mask:0xf bound_ctrl:1
	v_add_f32_dpp v160, v160, v160 row_half_mirror row_mask:0xf bank_mask:0xf bound_ctrl:1
	v_add_f32_dpp v161, v161, v161 row_half_mirror row_mask:0xf bank_mask:0xf bound_ctrl:1
	s_waitcnt lgkmcnt(12)
	v_pk_fma_f32 v[72:73], v[32:33], v[172:173], v[218:219] op_sel_hi:[1,0,1]
	v_pk_fma_f32 v[80:81], v[32:33], v[174:175], v[226:227] op_sel_hi:[1,0,1]
	v_pk_fma_f32 v[74:75], v[34:35], v[172:173], v[220:221] op_sel_hi:[1,0,1]
	v_pk_fma_f32 v[82:83], v[34:35], v[174:175], v[228:229] op_sel_hi:[1,0,1]
	v_pk_fma_f32 v[76:77], v[36:37], v[172:173], v[222:223] op_sel_hi:[1,0,1]
	v_pk_fma_f32 v[84:85], v[36:37], v[174:175], v[230:231] op_sel_hi:[1,0,1]
	v_pk_fma_f32 v[78:79], v[38:39], v[172:173], v[224:225] op_sel_hi:[1,0,1]
	v_pk_fma_f32 v[86:87], v[38:39], v[174:175], v[234:235] op_sel_hi:[1,0,1]
	ds_write_b64 v1, v[160:161] offset:56576
	s_waitcnt lgkmcnt(8)
	v_pk_mul_f32 v[164:165], v[72:73], v[176:177]
	v_pk_mul_f32 v[166:167], v[80:81], v[176:177]
	ds_read_b128 v[208:211], v2 offset:19456
	v_pk_mul_f32 v[168:169], v[72:73], v[48:49]
	v_pk_mul_f32 v[170:171], v[80:81], v[48:49]
	ds_read_b128 v[212:215], v2 offset:19472
	v_pk_fma_f32 v[164:165], v[74:75], v[178:179], v[164:165]
	v_pk_fma_f32 v[166:167], v[82:83], v[178:179], v[166:167]
	ds_read_b128 v[4:7], v2 offset:7424
	v_pk_fma_f32 v[168:169], v[74:75], v[50:51], v[168:169]
	v_pk_fma_f32 v[170:171], v[82:83], v[50:51], v[170:171]
	ds_read_b128 v[8:11], v2 offset:7440
	v_pk_fma_f32 v[164:165], v[76:77], v[180:181], v[164:165]
	v_pk_fma_f32 v[166:167], v[84:85], v[180:181], v[166:167]
	ds_read_b128 v[40:43], v2 offset:15616
	v_pk_fma_f32 v[168:169], v[76:77], v[52:53], v[168:169]
	v_pk_fma_f32 v[170:171], v[84:85], v[52:53], v[170:171]
	ds_read_b128 v[44:47], v2 offset:15632
	v_pk_fma_f32 v[164:165], v[78:79], v[182:183], v[164:165]
	v_pk_fma_f32 v[166:167], v[86:87], v[182:183], v[166:167]
	ds_read_b64 v[26:27], v3 offset:44288
	v_pk_fma_f32 v[168:169], v[78:79], v[54:55], v[168:169]
	v_pk_fma_f32 v[170:171], v[86:87], v[54:55], v[170:171]
	ds_read_b128 v[12:15], v2 offset:3328
	s_waitcnt lgkmcnt(13)
	v_pk_mul_f32 v[218:219], v[216:217], v[200:201] op_sel_hi:[0,1]
	v_pk_mul_f32 v[226:227], v[216:217], v[200:201] op_sel:[1,0]
	ds_read_b128 v[28:31], v2 offset:3344
	v_pk_mul_f32 v[220:221], v[216:217], v[202:203] op_sel_hi:[0,1]
	v_pk_mul_f32 v[228:229], v[216:217], v[202:203] op_sel:[1,0]
	ds_read_b128 v[32:35], v2 offset:11520
	v_pk_mul_f32 v[222:223], v[216:217], v[204:205] op_sel_hi:[0,1]
	v_pk_mul_f32 v[230:231], v[216:217], v[204:205] op_sel:[1,0]
	ds_read_b128 v[36:39], v2 offset:11536
	v_pk_mul_f32 v[224:225], v[216:217], v[206:207] op_sel_hi:[0,1]
	v_pk_mul_f32 v[234:235], v[216:217], v[206:207] op_sel:[1,0]
	v_add_f32_e32 v172, v164, v165
	v_add_f32_e32 v174, v166, v167
	v_add_f32_e32 v160, v168, v169
	v_add_f32_e32 v161, v170, v171
	s_waitcnt lgkmcnt(14)
	v_pk_fma_f32 v[218:219], v[72:73], v[184:185], v[218:219]
	v_pk_fma_f32 v[226:227], v[80:81], v[184:185], v[226:227]
	v_pk_fma_f32 v[220:221], v[74:75], v[186:187], v[220:221]
	v_pk_fma_f32 v[228:229], v[82:83], v[186:187], v[228:229]
	v_add_f32_dpp v172, v172, v172 quad_perm:[1,0,3,2] row_mask:0xf bank_mask:0xf bound_ctrl:1
	v_add_f32_dpp v174, v174, v174 quad_perm:[1,0,3,2] row_mask:0xf bank_mask:0xf bound_ctrl:1
	v_add_f32_dpp v160, v160, v160 quad_perm:[1,0,3,2] row_mask:0xf bank_mask:0xf bound_ctrl:1
	v_add_f32_dpp v161, v161, v161 quad_perm:[1,0,3,2] row_mask:0xf bank_mask:0xf bound_ctrl:1
	v_pk_fma_f32 v[222:223], v[76:77], v[188:189], v[222:223]
	v_pk_fma_f32 v[230:231], v[84:85], v[188:189], v[230:231]
	v_pk_fma_f32 v[224:225], v[78:79], v[190:191], v[224:225]
	v_pk_fma_f32 v[234:235], v[86:87], v[190:191], v[234:235]
	v_add_f32_dpp v172, v172, v172 quad_perm:[2,3,0,1] row_mask:0xf bank_mask:0xf bound_ctrl:1
	v_add_f32_dpp v174, v174, v174 quad_perm:[2,3,0,1] row_mask:0xf bank_mask:0xf bound_ctrl:1
	v_add_f32_dpp v160, v160, v160 quad_perm:[2,3,0,1] row_mask:0xf bank_mask:0xf bound_ctrl:1
	v_add_f32_dpp v161, v161, v161 quad_perm:[2,3,0,1] row_mask:0xf bank_mask:0xf bound_ctrl:1
	v_add_f32_dpp v172, v172, v172 row_half_mirror row_mask:0xf bank_mask:0xf bound_ctrl:1
	v_add_f32_dpp v174, v174, v174 row_half_mirror row_mask:0xf bank_mask:0xf bound_ctrl:1
	v_add_f32_dpp v160, v160, v160 row_half_mirror row_mask:0xf bank_mask:0xf bound_ctrl:1
	v_add_f32_dpp v161, v161, v161 row_half_mirror row_mask:0xf bank_mask:0xf bound_ctrl:1
	s_waitcnt lgkmcnt(12)
	v_pk_fma_f32 v[72:73], v[192:193], v[172:173], v[218:219] op_sel_hi:[1,0,1]
	v_pk_fma_f32 v[80:81], v[192:193], v[174:175], v[226:227] op_sel_hi:[1,0,1]
	v_pk_fma_f32 v[74:75], v[194:195], v[172:173], v[220:221] op_sel_hi:[1,0,1]
	v_pk_fma_f32 v[82:83], v[194:195], v[174:175], v[228:229] op_sel_hi:[1,0,1]
	v_pk_fma_f32 v[76:77], v[196:197], v[172:173], v[222:223] op_sel_hi:[1,0,1]
	v_pk_fma_f32 v[84:85], v[196:197], v[174:175], v[230:231] op_sel_hi:[1,0,1]
	v_pk_fma_f32 v[78:79], v[198:199], v[172:173], v[224:225] op_sel_hi:[1,0,1]
	v_pk_fma_f32 v[86:87], v[198:199], v[174:175], v[234:235] op_sel_hi:[1,0,1]
	ds_write_b64 v1, v[160:161] offset:56832
	s_waitcnt lgkmcnt(8)
	v_pk_mul_f32 v[164:165], v[72:73], v[4:5]
	v_pk_mul_f32 v[166:167], v[80:81], v[4:5]
	ds_read_b128 v[48:51], v2 offset:19712
	v_pk_mul_f32 v[168:169], v[72:73], v[208:209]
	v_pk_mul_f32 v[170:171], v[80:81], v[208:209]
	ds_read_b128 v[52:55], v2 offset:19728
	v_pk_fma_f32 v[164:165], v[74:75], v[6:7], v[164:165]
	v_pk_fma_f32 v[166:167], v[82:83], v[6:7], v[166:167]
	ds_read_b128 v[176:179], v2 offset:7680
	v_pk_fma_f32 v[168:169], v[74:75], v[210:211], v[168:169]
	v_pk_fma_f32 v[170:171], v[82:83], v[210:211], v[170:171]
	ds_read_b128 v[180:183], v2 offset:7696
	v_pk_fma_f32 v[164:165], v[76:77], v[8:9], v[164:165]
	v_pk_fma_f32 v[166:167], v[84:85], v[8:9], v[166:167]
	ds_read_b128 v[200:203], v2 offset:15872
	v_pk_fma_f32 v[168:169], v[76:77], v[212:213], v[168:169]
	v_pk_fma_f32 v[170:171], v[84:85], v[212:213], v[170:171]
	ds_read_b128 v[204:207], v2 offset:15888
	v_pk_fma_f32 v[164:165], v[78:79], v[10:11], v[164:165]
	v_pk_fma_f32 v[166:167], v[86:87], v[10:11], v[166:167]
	ds_read_b64 v[216:217], v3 offset:44544
	v_pk_fma_f32 v[168:169], v[78:79], v[214:215], v[168:169]
	v_pk_fma_f32 v[170:171], v[86:87], v[214:215], v[170:171]
	ds_read_b128 v[184:187], v2 offset:3584
	s_waitcnt lgkmcnt(13)
	v_pk_mul_f32 v[218:219], v[26:27], v[40:41] op_sel_hi:[0,1]
	v_pk_mul_f32 v[226:227], v[26:27], v[40:41] op_sel:[1,0]
	ds_read_b128 v[188:191], v2 offset:3600
	v_pk_mul_f32 v[220:221], v[26:27], v[42:43] op_sel_hi:[0,1]
	v_pk_mul_f32 v[228:229], v[26:27], v[42:43] op_sel:[1,0]
	ds_read_b128 v[192:195], v2 offset:11776
	v_pk_mul_f32 v[222:223], v[26:27], v[44:45] op_sel_hi:[0,1]
	v_pk_mul_f32 v[230:231], v[26:27], v[44:45] op_sel:[1,0]
	ds_read_b128 v[196:199], v2 offset:11792
	v_pk_mul_f32 v[224:225], v[26:27], v[46:47] op_sel_hi:[0,1]
	v_pk_mul_f32 v[234:235], v[26:27], v[46:47] op_sel:[1,0]
	v_add_f32_e32 v172, v164, v165
	v_add_f32_e32 v174, v166, v167
	v_add_f32_e32 v160, v168, v169
	v_add_f32_e32 v161, v170, v171
	s_waitcnt lgkmcnt(14)
	v_pk_fma_f32 v[218:219], v[72:73], v[12:13], v[218:219]
	v_pk_fma_f32 v[226:227], v[80:81], v[12:13], v[226:227]
	v_pk_fma_f32 v[220:221], v[74:75], v[14:15], v[220:221]
	v_pk_fma_f32 v[228:229], v[82:83], v[14:15], v[228:229]
	v_add_f32_dpp v172, v172, v172 quad_perm:[1,0,3,2] row_mask:0xf bank_mask:0xf bound_ctrl:1
	v_add_f32_dpp v174, v174, v174 quad_perm:[1,0,3,2] row_mask:0xf bank_mask:0xf bound_ctrl:1
	v_add_f32_dpp v160, v160, v160 quad_perm:[1,0,3,2] row_mask:0xf bank_mask:0xf bound_ctrl:1
	v_add_f32_dpp v161, v161, v161 quad_perm:[1,0,3,2] row_mask:0xf bank_mask:0xf bound_ctrl:1
	v_pk_fma_f32 v[222:223], v[76:77], v[28:29], v[222:223]
	v_pk_fma_f32 v[230:231], v[84:85], v[28:29], v[230:231]
	v_pk_fma_f32 v[224:225], v[78:79], v[30:31], v[224:225]
	v_pk_fma_f32 v[234:235], v[86:87], v[30:31], v[234:235]
	v_add_f32_dpp v172, v172, v172 quad_perm:[2,3,0,1] row_mask:0xf bank_mask:0xf bound_ctrl:1
	v_add_f32_dpp v174, v174, v174 quad_perm:[2,3,0,1] row_mask:0xf bank_mask:0xf bound_ctrl:1
	v_add_f32_dpp v160, v160, v160 quad_perm:[2,3,0,1] row_mask:0xf bank_mask:0xf bound_ctrl:1
	v_add_f32_dpp v161, v161, v161 quad_perm:[2,3,0,1] row_mask:0xf bank_mask:0xf bound_ctrl:1
	v_add_f32_dpp v172, v172, v172 row_half_mirror row_mask:0xf bank_mask:0xf bound_ctrl:1
	v_add_f32_dpp v174, v174, v174 row_half_mirror row_mask:0xf bank_mask:0xf bound_ctrl:1
	v_add_f32_dpp v160, v160, v160 row_half_mirror row_mask:0xf bank_mask:0xf bound_ctrl:1
	v_add_f32_dpp v161, v161, v161 row_half_mirror row_mask:0xf bank_mask:0xf bound_ctrl:1
	s_waitcnt lgkmcnt(12)
	v_pk_fma_f32 v[72:73], v[32:33], v[172:173], v[218:219] op_sel_hi:[1,0,1]
	v_pk_fma_f32 v[80:81], v[32:33], v[174:175], v[226:227] op_sel_hi:[1,0,1]
	v_pk_fma_f32 v[74:75], v[34:35], v[172:173], v[220:221] op_sel_hi:[1,0,1]
	v_pk_fma_f32 v[82:83], v[34:35], v[174:175], v[228:229] op_sel_hi:[1,0,1]
	v_pk_fma_f32 v[76:77], v[36:37], v[172:173], v[222:223] op_sel_hi:[1,0,1]
	v_pk_fma_f32 v[84:85], v[36:37], v[174:175], v[230:231] op_sel_hi:[1,0,1]
	v_pk_fma_f32 v[78:79], v[38:39], v[172:173], v[224:225] op_sel_hi:[1,0,1]
	v_pk_fma_f32 v[86:87], v[38:39], v[174:175], v[234:235] op_sel_hi:[1,0,1]
	ds_write_b64 v1, v[160:161] offset:57088
	s_waitcnt lgkmcnt(8)
	v_pk_mul_f32 v[164:165], v[72:73], v[176:177]
	v_pk_mul_f32 v[166:167], v[80:81], v[176:177]
	ds_read_b128 v[208:211], v2 offset:19968
	v_pk_mul_f32 v[168:169], v[72:73], v[48:49]
	v_pk_mul_f32 v[170:171], v[80:81], v[48:49]
	ds_read_b128 v[212:215], v2 offset:19984
	v_pk_fma_f32 v[164:165], v[74:75], v[178:179], v[164:165]
	v_pk_fma_f32 v[166:167], v[82:83], v[178:179], v[166:167]
	ds_read_b128 v[4:7], v2 offset:7936
	v_pk_fma_f32 v[168:169], v[74:75], v[50:51], v[168:169]
	v_pk_fma_f32 v[170:171], v[82:83], v[50:51], v[170:171]
	ds_read_b128 v[8:11], v2 offset:7952
	v_pk_fma_f32 v[164:165], v[76:77], v[180:181], v[164:165]
	v_pk_fma_f32 v[166:167], v[84:85], v[180:181], v[166:167]
	ds_read_b128 v[40:43], v2 offset:16128
	v_pk_fma_f32 v[168:169], v[76:77], v[52:53], v[168:169]
	v_pk_fma_f32 v[170:171], v[84:85], v[52:53], v[170:171]
	ds_read_b128 v[44:47], v2 offset:16144
	v_pk_fma_f32 v[164:165], v[78:79], v[182:183], v[164:165]
	v_pk_fma_f32 v[166:167], v[86:87], v[182:183], v[166:167]
	ds_read_b64 v[26:27], v3 offset:44800
	v_pk_fma_f32 v[168:169], v[78:79], v[54:55], v[168:169]
	v_pk_fma_f32 v[170:171], v[86:87], v[54:55], v[170:171]
	ds_read_b128 v[12:15], v2 offset:3840
	s_waitcnt lgkmcnt(13)
	v_pk_mul_f32 v[218:219], v[216:217], v[200:201] op_sel_hi:[0,1]
	v_pk_mul_f32 v[226:227], v[216:217], v[200:201] op_sel:[1,0]
	ds_read_b128 v[28:31], v2 offset:3856
	v_pk_mul_f32 v[220:221], v[216:217], v[202:203] op_sel_hi:[0,1]
	v_pk_mul_f32 v[228:229], v[216:217], v[202:203] op_sel:[1,0]
	ds_read_b128 v[32:35], v2 offset:12032
	v_pk_mul_f32 v[222:223], v[216:217], v[204:205] op_sel_hi:[0,1]
	v_pk_mul_f32 v[230:231], v[216:217], v[204:205] op_sel:[1,0]
	ds_read_b128 v[36:39], v2 offset:12048
	v_pk_mul_f32 v[224:225], v[216:217], v[206:207] op_sel_hi:[0,1]
	v_pk_mul_f32 v[234:235], v[216:217], v[206:207] op_sel:[1,0]
	v_add_f32_e32 v172, v164, v165
	v_add_f32_e32 v174, v166, v167
	v_add_f32_e32 v160, v168, v169
	v_add_f32_e32 v161, v170, v171
	s_waitcnt lgkmcnt(14)
	v_pk_fma_f32 v[218:219], v[72:73], v[184:185], v[218:219]
	v_pk_fma_f32 v[226:227], v[80:81], v[184:185], v[226:227]
	v_pk_fma_f32 v[220:221], v[74:75], v[186:187], v[220:221]
	v_pk_fma_f32 v[228:229], v[82:83], v[186:187], v[228:229]
	v_add_f32_dpp v172, v172, v172 quad_perm:[1,0,3,2] row_mask:0xf bank_mask:0xf bound_ctrl:1
	v_add_f32_dpp v174, v174, v174 quad_perm:[1,0,3,2] row_mask:0xf bank_mask:0xf bound_ctrl:1
	v_add_f32_dpp v160, v160, v160 quad_perm:[1,0,3,2] row_mask:0xf bank_mask:0xf bound_ctrl:1
	v_add_f32_dpp v161, v161, v161 quad_perm:[1,0,3,2] row_mask:0xf bank_mask:0xf bound_ctrl:1
	v_pk_fma_f32 v[222:223], v[76:77], v[188:189], v[222:223]
	v_pk_fma_f32 v[230:231], v[84:85], v[188:189], v[230:231]
	v_pk_fma_f32 v[224:225], v[78:79], v[190:191], v[224:225]
	v_pk_fma_f32 v[234:235], v[86:87], v[190:191], v[234:235]
	v_add_f32_dpp v172, v172, v172 quad_perm:[2,3,0,1] row_mask:0xf bank_mask:0xf bound_ctrl:1
	v_add_f32_dpp v174, v174, v174 quad_perm:[2,3,0,1] row_mask:0xf bank_mask:0xf bound_ctrl:1
	v_add_f32_dpp v160, v160, v160 quad_perm:[2,3,0,1] row_mask:0xf bank_mask:0xf bound_ctrl:1
	v_add_f32_dpp v161, v161, v161 quad_perm:[2,3,0,1] row_mask:0xf bank_mask:0xf bound_ctrl:1
	v_add_f32_dpp v172, v172, v172 row_half_mirror row_mask:0xf bank_mask:0xf bound_ctrl:1
	v_add_f32_dpp v174, v174, v174 row_half_mirror row_mask:0xf bank_mask:0xf bound_ctrl:1
	v_add_f32_dpp v160, v160, v160 row_half_mirror row_mask:0xf bank_mask:0xf bound_ctrl:1
	v_add_f32_dpp v161, v161, v161 row_half_mirror row_mask:0xf bank_mask:0xf bound_ctrl:1
	s_waitcnt lgkmcnt(12)
	v_pk_fma_f32 v[72:73], v[192:193], v[172:173], v[218:219] op_sel_hi:[1,0,1]
	v_pk_fma_f32 v[80:81], v[192:193], v[174:175], v[226:227] op_sel_hi:[1,0,1]
	v_pk_fma_f32 v[74:75], v[194:195], v[172:173], v[220:221] op_sel_hi:[1,0,1]
	v_pk_fma_f32 v[82:83], v[194:195], v[174:175], v[228:229] op_sel_hi:[1,0,1]
	v_pk_fma_f32 v[76:77], v[196:197], v[172:173], v[222:223] op_sel_hi:[1,0,1]
	v_pk_fma_f32 v[84:85], v[196:197], v[174:175], v[230:231] op_sel_hi:[1,0,1]
	v_pk_fma_f32 v[78:79], v[198:199], v[172:173], v[224:225] op_sel_hi:[1,0,1]
	v_pk_fma_f32 v[86:87], v[198:199], v[174:175], v[234:235] op_sel_hi:[1,0,1]
	ds_write_b64 v1, v[160:161] offset:57344
	s_waitcnt lgkmcnt(8)
	v_pk_mul_f32 v[164:165], v[72:73], v[4:5]
	v_pk_mul_f32 v[166:167], v[80:81], v[4:5]
	ds_read_b128 v[48:51], v2 offset:20224
	v_pk_mul_f32 v[168:169], v[72:73], v[208:209]
	v_pk_mul_f32 v[170:171], v[80:81], v[208:209]
	ds_read_b128 v[52:55], v2 offset:20240
	v_pk_fma_f32 v[164:165], v[74:75], v[6:7], v[164:165]
	v_pk_fma_f32 v[166:167], v[82:83], v[6:7], v[166:167]
	v_pk_fma_f32 v[168:169], v[74:75], v[210:211], v[168:169]
	v_pk_fma_f32 v[170:171], v[82:83], v[210:211], v[170:171]
	v_pk_fma_f32 v[164:165], v[76:77], v[8:9], v[164:165]
	v_pk_fma_f32 v[166:167], v[84:85], v[8:9], v[166:167]
	v_pk_fma_f32 v[168:169], v[76:77], v[212:213], v[168:169]
	v_pk_fma_f32 v[170:171], v[84:85], v[212:213], v[170:171]
	v_pk_fma_f32 v[164:165], v[78:79], v[10:11], v[164:165]
	v_pk_fma_f32 v[166:167], v[86:87], v[10:11], v[166:167]
	v_pk_fma_f32 v[168:169], v[78:79], v[214:215], v[168:169]
	v_pk_fma_f32 v[170:171], v[86:87], v[214:215], v[170:171]
	s_waitcnt lgkmcnt(7)
	v_pk_mul_f32 v[218:219], v[26:27], v[40:41] op_sel_hi:[0,1]
	v_pk_mul_f32 v[226:227], v[26:27], v[40:41] op_sel:[1,0]
	v_pk_mul_f32 v[220:221], v[26:27], v[42:43] op_sel_hi:[0,1]
	v_pk_mul_f32 v[228:229], v[26:27], v[42:43] op_sel:[1,0]
	v_pk_mul_f32 v[222:223], v[26:27], v[44:45] op_sel_hi:[0,1]
	v_pk_mul_f32 v[230:231], v[26:27], v[44:45] op_sel:[1,0]
	v_pk_mul_f32 v[224:225], v[26:27], v[46:47] op_sel_hi:[0,1]
	v_pk_mul_f32 v[234:235], v[26:27], v[46:47] op_sel:[1,0]
	v_add_f32_e32 v172, v164, v165
	v_add_f32_e32 v174, v166, v167
	v_add_f32_e32 v160, v168, v169
	v_add_f32_e32 v161, v170, v171
	s_waitcnt lgkmcnt(5)
	v_pk_fma_f32 v[218:219], v[72:73], v[12:13], v[218:219]
	v_pk_fma_f32 v[226:227], v[80:81], v[12:13], v[226:227]
	v_pk_fma_f32 v[220:221], v[74:75], v[14:15], v[220:221]
	v_pk_fma_f32 v[228:229], v[82:83], v[14:15], v[228:229]
	v_add_f32_dpp v172, v172, v172 quad_perm:[1,0,3,2] row_mask:0xf bank_mask:0xf bound_ctrl:1
	v_add_f32_dpp v174, v174, v174 quad_perm:[1,0,3,2] row_mask:0xf bank_mask:0xf bound_ctrl:1
	v_add_f32_dpp v160, v160, v160 quad_perm:[1,0,3,2] row_mask:0xf bank_mask:0xf bound_ctrl:1
	v_add_f32_dpp v161, v161, v161 quad_perm:[1,0,3,2] row_mask:0xf bank_mask:0xf bound_ctrl:1
	v_pk_fma_f32 v[222:223], v[76:77], v[28:29], v[222:223]
	v_pk_fma_f32 v[230:231], v[84:85], v[28:29], v[230:231]
	v_pk_fma_f32 v[224:225], v[78:79], v[30:31], v[224:225]
	v_pk_fma_f32 v[234:235], v[86:87], v[30:31], v[234:235]
	v_add_f32_dpp v172, v172, v172 quad_perm:[2,3,0,1] row_mask:0xf bank_mask:0xf bound_ctrl:1
	v_add_f32_dpp v174, v174, v174 quad_perm:[2,3,0,1] row_mask:0xf bank_mask:0xf bound_ctrl:1
	v_add_f32_dpp v160, v160, v160 quad_perm:[2,3,0,1] row_mask:0xf bank_mask:0xf bound_ctrl:1
	v_add_f32_dpp v161, v161, v161 quad_perm:[2,3,0,1] row_mask:0xf bank_mask:0xf bound_ctrl:1
	v_add_f32_dpp v172, v172, v172 row_half_mirror row_mask:0xf bank_mask:0xf bound_ctrl:1
	v_add_f32_dpp v174, v174, v174 row_half_mirror row_mask:0xf bank_mask:0xf bound_ctrl:1
	v_add_f32_dpp v160, v160, v160 row_half_mirror row_mask:0xf bank_mask:0xf bound_ctrl:1
	v_add_f32_dpp v161, v161, v161 row_half_mirror row_mask:0xf bank_mask:0xf bound_ctrl:1
	s_waitcnt lgkmcnt(3)
	v_pk_fma_f32 v[72:73], v[32:33], v[172:173], v[218:219] op_sel_hi:[1,0,1]
	v_pk_fma_f32 v[80:81], v[32:33], v[174:175], v[226:227] op_sel_hi:[1,0,1]
	v_pk_fma_f32 v[74:75], v[34:35], v[172:173], v[220:221] op_sel_hi:[1,0,1]
	v_pk_fma_f32 v[82:83], v[34:35], v[174:175], v[228:229] op_sel_hi:[1,0,1]
	v_pk_fma_f32 v[76:77], v[36:37], v[172:173], v[222:223] op_sel_hi:[1,0,1]
	v_pk_fma_f32 v[84:85], v[36:37], v[174:175], v[230:231] op_sel_hi:[1,0,1]
	v_pk_fma_f32 v[78:79], v[38:39], v[172:173], v[224:225] op_sel_hi:[1,0,1]
	v_pk_fma_f32 v[86:87], v[38:39], v[174:175], v[234:235] op_sel_hi:[1,0,1]
	ds_write_b64 v1, v[160:161] offset:57600
	s_waitcnt lgkmcnt(1)
	v_pk_mul_f32 v[168:169], v[72:73], v[48:49]
	v_pk_mul_f32 v[170:171], v[80:81], v[48:49]
	v_pk_fma_f32 v[168:169], v[74:75], v[50:51], v[168:169]
	v_pk_fma_f32 v[170:171], v[82:83], v[50:51], v[170:171]
	v_pk_fma_f32 v[168:169], v[76:77], v[52:53], v[168:169]
	v_pk_fma_f32 v[170:171], v[84:85], v[52:53], v[170:171]
	v_pk_fma_f32 v[168:169], v[78:79], v[54:55], v[168:169]
	v_pk_fma_f32 v[170:171], v[86:87], v[54:55], v[170:171]
	v_add_f32_e32 v160, v168, v169
	v_add_f32_e32 v161, v170, v171
	s_nop 0
	v_add_f32_dpp v160, v160, v160 quad_perm:[1,0,3,2] row_mask:0xf bank_mask:0xf bound_ctrl:1
	v_add_f32_dpp v161, v161, v161 quad_perm:[1,0,3,2] row_mask:0xf bank_mask:0xf bound_ctrl:1
	s_nop 0
	v_add_f32_dpp v160, v160, v160 quad_perm:[2,3,0,1] row_mask:0xf bank_mask:0xf bound_ctrl:1
	v_add_f32_dpp v161, v161, v161 quad_perm:[2,3,0,1] row_mask:0xf bank_mask:0xf bound_ctrl:1
	s_nop 0
	v_add_f32_dpp v160, v160, v160 row_half_mirror row_mask:0xf bank_mask:0xf bound_ctrl:1
	v_add_f32_dpp v161, v161, v161 row_half_mirror row_mask:0xf bank_mask:0xf bound_ctrl:1
	ds_write_b64 v1, v[160:161] offset:57856
	s_add_i32 s3, s2, 1
	s_mov_b64 s[36:37], 0
